# K-loop MFMA blocks: dropped the back-to-back s_setprio 0 / s_setprio 1 pair between the two halves of a block
# speedup vs baseline: 1.0011x; 1.0011x over previous
.LBB0_42:
	s_add_u32 s8, s4, s2
	s_addc_u32 s9, s5, 0
	s_add_u32 s3, s8, 0x100
	s_addc_u32 s10, s9, 0
	s_and_b64 s[6:7], s[84:85], exec
	s_cselect_b32 s7, s87, s10
	s_cselect_b32 s6, s86, s3
	s_add_u32 s2, s36, s2
	s_addc_u32 s3, s37, 0
	s_add_u32 s10, s2, 0x100
	ds_read_b128 v[128:131], v221
	ds_read_b128 v[132:135], v222
	ds_read_b128 v[136:139], v223
	ds_read_b128 v[140:143], v224
	ds_read_b128 v[144:147], v225
	ds_read_b128 v[148:151], v226
	ds_read_b128 v[152:155], v227
	ds_read_b128 v[156:159], v228
	s_addc_u32 s11, s3, 0
	s_and_b64 s[2:3], s[84:85], exec
	s_cselect_b32 vcc_hi, s89, s11
	s_cselect_b32 vcc_lo, s88, s10
	s_add_u32 s10, s8, 0x30080
	s_addc_u32 s11, s9, 0
	s_add_u32 s8, vcc_lo, 0x10000
	s_addc_u32 s9, vcc_hi, 0
	s_add_u32 s2, s6, 0x30000
	s_addc_u32 s3, s7, 0
	s_add_u32 s84, vcc_lo, 0x10080
	s_addc_u32 s85, vcc_hi, 0
	s_mov_b32 m0, s19
	ds_read_b128 v[160:163], v219
	ds_read_b128 v[164:167], v219 offset:1024
	ds_read_b128 v[168:171], v219 offset:2048
	ds_read_b128 v[172:175], v219 offset:3072
	ds_read_b128 v[198:201], v219 offset:4096
	ds_read_b128 v[202:205], v219 offset:5120
	ds_read_b128 v[238:241], v219 offset:6144
	ds_read_b128 v[242:245], v219 offset:7168
	global_load_lds_dwordx4 v192, s[10:11]
	s_mov_b32 m0, s74
	s_nop 0
	global_load_lds_dwordx4 v188, s[10:11]
	s_waitcnt vmcnt(8)
	s_waitcnt lgkmcnt(0)
	s_barrier
	s_setprio 1
	s_waitcnt lgkmcnt(0)
	v_mfma_f32_16x16x32_bf16 v[104:107], v[128:131], v[160:163], v[104:107]
	v_mfma_f32_16x16x32_bf16 v[124:127], v[136:139], v[160:163], v[124:127]
	v_mfma_f32_16x16x32_bf16 v[96:99], v[128:131], v[168:171], v[96:99]
	v_mfma_f32_16x16x32_bf16 v[120:123], v[136:139], v[168:171], v[120:123]
	v_mfma_f32_16x16x32_bf16 v[88:91], v[128:131], v[198:201], v[88:91]
	v_mfma_f32_16x16x32_bf16 v[116:119], v[136:139], v[198:201], v[116:119]
	v_mfma_f32_16x16x32_bf16 v[80:83], v[128:131], v[238:241], v[80:83]
	v_mfma_f32_16x16x32_bf16 v[112:115], v[136:139], v[238:241], v[112:115]
	v_mfma_f32_16x16x32_bf16 v[104:107], v[132:135], v[164:167], v[104:107]
	v_mfma_f32_16x16x32_bf16 v[124:127], v[140:143], v[164:167], v[124:127]
	v_mfma_f32_16x16x32_bf16 v[96:99], v[132:135], v[172:175], v[96:99]
	v_mfma_f32_16x16x32_bf16 v[120:123], v[140:143], v[172:175], v[120:123]
	v_mfma_f32_16x16x32_bf16 v[88:91], v[132:135], v[202:205], v[88:91]
	v_mfma_f32_16x16x32_bf16 v[116:119], v[140:143], v[202:205], v[116:119]
	v_mfma_f32_16x16x32_bf16 v[80:83], v[132:135], v[242:245], v[80:83]
	v_mfma_f32_16x16x32_bf16 v[112:115], v[140:143], v[242:245], v[112:115]
	v_mfma_f32_16x16x32_bf16 v[72:75], v[144:147], v[160:163], v[72:75]
	v_mfma_f32_16x16x32_bf16 v[108:111], v[152:155], v[160:163], v[108:111]
	v_mfma_f32_16x16x32_bf16 v[64:67], v[144:147], v[168:171], v[64:67]
	v_mfma_f32_16x16x32_bf16 v[100:103], v[152:155], v[168:171], v[100:103]
	v_mfma_f32_16x16x32_bf16 v[56:59], v[144:147], v[198:201], v[56:59]
	v_mfma_f32_16x16x32_bf16 v[92:95], v[152:155], v[198:201], v[92:95]
	v_mfma_f32_16x16x32_bf16 v[48:51], v[144:147], v[238:241], v[48:51]
	v_mfma_f32_16x16x32_bf16 v[84:87], v[152:155], v[238:241], v[84:87]
	v_mfma_f32_16x16x32_bf16 v[72:75], v[148:151], v[164:167], v[72:75]
	v_mfma_f32_16x16x32_bf16 v[108:111], v[156:159], v[164:167], v[108:111]
	v_mfma_f32_16x16x32_bf16 v[64:67], v[148:151], v[172:175], v[64:67]
	v_mfma_f32_16x16x32_bf16 v[100:103], v[156:159], v[172:175], v[100:103]
	v_mfma_f32_16x16x32_bf16 v[56:59], v[148:151], v[202:205], v[56:59]
	v_mfma_f32_16x16x32_bf16 v[92:95], v[156:159], v[202:205], v[92:95]
	v_mfma_f32_16x16x32_bf16 v[48:51], v[148:151], v[242:245], v[48:51]
	v_mfma_f32_16x16x32_bf16 v[84:87], v[156:159], v[242:245], v[84:87]
	s_setprio 0
	s_barrier
	s_mov_b32 m0, s23
	v_lshl_add_u64 v[246:247], vcc, 0, v[190:191]
	ds_read_b128 v[160:163], v219 offset:16384
	ds_read_b128 v[164:167], v219 offset:17408
	ds_read_b128 v[168:171], v219 offset:18432
	ds_read_b128 v[172:175], v219 offset:19456
	ds_read_b128 v[198:201], v219 offset:20480
	ds_read_b128 v[202:205], v219 offset:21504
	ds_read_b128 v[238:241], v219 offset:22528
	ds_read_b128 v[242:245], v219 offset:23552
	global_load_lds_dwordx4 v[246:247], off
	v_lshl_add_u64 v[248:249], vcc, 0, v[186:187]
	s_mov_b32 m0, s91
	s_nop 0
	global_load_lds_dwordx4 v[248:249], off
	s_mov_b32 m0, s21
	v_lshl_add_u64 v[252:253], s[6:7], 0, v[188:189]
	global_load_lds_dwordx4 v190, s[8:9]
	s_mov_b32 m0, s27
	s_nop 0
	global_load_lds_dwordx4 v186, s[8:9]
	v_lshl_add_u64 v[250:251], s[6:7], 0, v[192:193]
	s_mov_b32 m0, s43
	s_nop 0
	global_load_lds_dwordx4 v[250:251], off
	s_mov_b32 m0, s26
	s_nop 0
	global_load_lds_dwordx4 v[252:253], off
	s_waitcnt vmcnt(8)
	s_waitcnt lgkmcnt(0)
	s_barrier
	s_setprio 1
	s_waitcnt lgkmcnt(0)
	v_mfma_f32_16x16x32_bf16 v[40:43], v[128:131], v[160:163], v[40:43]
	v_mfma_f32_16x16x32_bf16 v[76:79], v[136:139], v[160:163], v[76:79]
	v_mfma_f32_16x16x32_bf16 v[32:35], v[128:131], v[168:171], v[32:35]
	v_mfma_f32_16x16x32_bf16 v[68:71], v[136:139], v[168:171], v[68:71]
	v_mfma_f32_16x16x32_bf16 v[24:27], v[128:131], v[198:201], v[24:27]
	v_mfma_f32_16x16x32_bf16 v[60:63], v[136:139], v[198:201], v[60:63]
	v_mfma_f32_16x16x32_bf16 v[20:23], v[128:131], v[238:241], v[20:23]
	v_mfma_f32_16x16x32_bf16 v[52:55], v[136:139], v[238:241], v[52:55]
	v_mfma_f32_16x16x32_bf16 v[40:43], v[132:135], v[164:167], v[40:43]
	v_mfma_f32_16x16x32_bf16 v[76:79], v[140:143], v[164:167], v[76:79]
	v_mfma_f32_16x16x32_bf16 v[32:35], v[132:135], v[172:175], v[32:35]
	v_mfma_f32_16x16x32_bf16 v[68:71], v[140:143], v[172:175], v[68:71]
	v_mfma_f32_16x16x32_bf16 v[24:27], v[132:135], v[202:205], v[24:27]
	v_mfma_f32_16x16x32_bf16 v[60:63], v[140:143], v[202:205], v[60:63]
	v_mfma_f32_16x16x32_bf16 v[20:23], v[132:135], v[242:245], v[20:23]
	v_mfma_f32_16x16x32_bf16 v[52:55], v[140:143], v[242:245], v[52:55]
	v_mfma_f32_16x16x32_bf16 v[16:19], v[144:147], v[160:163], v[16:19]
	v_mfma_f32_16x16x32_bf16 v[44:47], v[152:155], v[160:163], v[44:47]
	v_mfma_f32_16x16x32_bf16 v[12:15], v[144:147], v[168:171], v[12:15]
	v_mfma_f32_16x16x32_bf16 v[36:39], v[152:155], v[168:171], v[36:39]
	v_mfma_f32_16x16x32_bf16 v[4:7], v[144:147], v[198:201], v[4:7]
	v_mfma_f32_16x16x32_bf16 v[28:31], v[152:155], v[198:201], v[28:31]
	v_mfma_f32_16x16x32_bf16 v[0:3], v[144:147], v[238:241], v[0:3]
	v_mfma_f32_16x16x32_bf16 v[8:11], v[152:155], v[238:241], v[8:11]
	v_mfma_f32_16x16x32_bf16 v[16:19], v[148:151], v[164:167], v[16:19]
	v_mfma_f32_16x16x32_bf16 v[44:47], v[156:159], v[164:167], v[44:47]
	v_mfma_f32_16x16x32_bf16 v[12:15], v[148:151], v[172:175], v[12:15]
	v_mfma_f32_16x16x32_bf16 v[36:39], v[156:159], v[172:175], v[36:39]
	v_mfma_f32_16x16x32_bf16 v[4:7], v[148:151], v[202:205], v[4:7]
	v_mfma_f32_16x16x32_bf16 v[28:31], v[156:159], v[202:205], v[28:31]
	v_mfma_f32_16x16x32_bf16 v[0:3], v[148:151], v[242:245], v[0:3]
	v_mfma_f32_16x16x32_bf16 v[8:11], v[156:159], v[242:245], v[8:11]
	s_setprio 0
	s_barrier
	ds_read_b128 v[128:131], v229
	ds_read_b128 v[132:135], v230
	ds_read_b128 v[136:139], v231
	ds_read_b128 v[140:143], v232
	ds_read_b128 v[144:147], v233
	ds_read_b128 v[148:151], v234
	ds_read_b128 v[152:155], v235
	ds_read_b128 v[156:159], v236
	s_mov_b32 m0, s29
	ds_read_b128 v[160:163], v219 offset:32768
	ds_read_b128 v[164:167], v219 offset:33792
	ds_read_b128 v[168:171], v219 offset:34816
	ds_read_b128 v[172:175], v219 offset:35840
	ds_read_b128 v[198:201], v219 offset:36864
	ds_read_b128 v[202:205], v219 offset:37888
	ds_read_b128 v[238:241], v219 offset:38912
	ds_read_b128 v[242:245], v219 offset:39936
	global_load_lds_dwordx4 v192, s[2:3]
	s_mov_b32 m0, s28
	s_nop 0
	global_load_lds_dwordx4 v188, s[2:3]
	s_waitcnt vmcnt(8)
	s_waitcnt lgkmcnt(0)
	s_barrier
	s_setprio 1
	s_waitcnt lgkmcnt(0)
	v_mfma_f32_16x16x32_bf16 v[104:107], v[128:131], v[160:163], v[104:107]
	v_mfma_f32_16x16x32_bf16 v[124:127], v[136:139], v[160:163], v[124:127]
	v_mfma_f32_16x16x32_bf16 v[96:99], v[128:131], v[168:171], v[96:99]
	v_mfma_f32_16x16x32_bf16 v[120:123], v[136:139], v[168:171], v[120:123]
	v_mfma_f32_16x16x32_bf16 v[88:91], v[128:131], v[198:201], v[88:91]
	v_mfma_f32_16x16x32_bf16 v[116:119], v[136:139], v[198:201], v[116:119]
	v_mfma_f32_16x16x32_bf16 v[80:83], v[128:131], v[238:241], v[80:83]
	v_mfma_f32_16x16x32_bf16 v[112:115], v[136:139], v[238:241], v[112:115]
	v_mfma_f32_16x16x32_bf16 v[104:107], v[132:135], v[164:167], v[104:107]
	v_mfma_f32_16x16x32_bf16 v[124:127], v[140:143], v[164:167], v[124:127]
	v_mfma_f32_16x16x32_bf16 v[96:99], v[132:135], v[172:175], v[96:99]
	v_mfma_f32_16x16x32_bf16 v[120:123], v[140:143], v[172:175], v[120:123]
	v_mfma_f32_16x16x32_bf16 v[88:91], v[132:135], v[202:205], v[88:91]
	v_mfma_f32_16x16x32_bf16 v[116:119], v[140:143], v[202:205], v[116:119]
	v_mfma_f32_16x16x32_bf16 v[80:83], v[132:135], v[242:245], v[80:83]
	v_mfma_f32_16x16x32_bf16 v[112:115], v[140:143], v[242:245], v[112:115]
	v_mfma_f32_16x16x32_bf16 v[72:75], v[144:147], v[160:163], v[72:75]
	v_mfma_f32_16x16x32_bf16 v[108:111], v[152:155], v[160:163], v[108:111]
	v_mfma_f32_16x16x32_bf16 v[64:67], v[144:147], v[168:171], v[64:67]
	v_mfma_f32_16x16x32_bf16 v[100:103], v[152:155], v[168:171], v[100:103]
	v_mfma_f32_16x16x32_bf16 v[56:59], v[144:147], v[198:201], v[56:59]
	v_mfma_f32_16x16x32_bf16 v[92:95], v[152:155], v[198:201], v[92:95]
	v_mfma_f32_16x16x32_bf16 v[48:51], v[144:147], v[238:241], v[48:51]
	v_mfma_f32_16x16x32_bf16 v[84:87], v[152:155], v[238:241], v[84:87]
	v_mfma_f32_16x16x32_bf16 v[72:75], v[148:151], v[164:167], v[72:75]
	v_mfma_f32_16x16x32_bf16 v[108:111], v[156:159], v[164:167], v[108:111]
	v_mfma_f32_16x16x32_bf16 v[64:67], v[148:151], v[172:175], v[64:67]
	v_mfma_f32_16x16x32_bf16 v[100:103], v[156:159], v[172:175], v[100:103]
	v_mfma_f32_16x16x32_bf16 v[56:59], v[148:151], v[202:205], v[56:59]
	v_mfma_f32_16x16x32_bf16 v[92:95], v[156:159], v[202:205], v[92:95]
	v_mfma_f32_16x16x32_bf16 v[48:51], v[148:151], v[242:245], v[48:51]
	v_mfma_f32_16x16x32_bf16 v[84:87], v[156:159], v[242:245], v[84:87]
	s_setprio 0
	s_barrier
	s_mov_b32 m0, s31
	v_lshl_add_u64 v[214:215], v[246:247], 0, s[0:1]
	ds_read_b128 v[160:163], v219 offset:49152
	ds_read_b128 v[164:167], v219 offset:50176
	ds_read_b128 v[168:171], v219 offset:51200
	ds_read_b128 v[172:175], v219 offset:52224
	ds_read_b128 v[198:201], v219 offset:53248
	ds_read_b128 v[202:205], v219 offset:54272
	ds_read_b128 v[238:241], v219 offset:55296
	ds_read_b128 v[242:245], v219 offset:56320
	global_load_lds_dwordx4 v[214:215], off
	v_lshl_add_u64 v[214:215], v[248:249], 0, s[0:1]
	s_mov_b32 m0, s30
	s_nop 0
	global_load_lds_dwordx4 v[214:215], off
	s_mov_b32 m0, s95
	s_nop 0
	global_load_lds_dwordx4 v190, s[84:85]
	s_mov_b32 m0, s94
	s_nop 0
	global_load_lds_dwordx4 v186, s[84:85]
	v_lshl_add_u64 v[214:215], v[250:251], 0, s[0:1]
	s_mov_b32 m0, s35
	s_nop 0
	global_load_lds_dwordx4 v[214:215], off
	v_lshl_add_u64 v[214:215], v[252:253], 0, s[0:1]
	s_mov_b32 m0, s34
	s_nop 0
	global_load_lds_dwordx4 v[214:215], off
	s_waitcnt vmcnt(8)
	s_waitcnt lgkmcnt(0)
	s_barrier
	s_setprio 1
	s_waitcnt lgkmcnt(0)
	v_mfma_f32_16x16x32_bf16 v[40:43], v[128:131], v[160:163], v[40:43]
	v_mfma_f32_16x16x32_bf16 v[76:79], v[136:139], v[160:163], v[76:79]
	v_mfma_f32_16x16x32_bf16 v[32:35], v[128:131], v[168:171], v[32:35]
	v_mfma_f32_16x16x32_bf16 v[68:71], v[136:139], v[168:171], v[68:71]
	v_mfma_f32_16x16x32_bf16 v[24:27], v[128:131], v[198:201], v[24:27]
	v_mfma_f32_16x16x32_bf16 v[60:63], v[136:139], v[198:201], v[60:63]
	v_mfma_f32_16x16x32_bf16 v[20:23], v[128:131], v[238:241], v[20:23]
	v_mfma_f32_16x16x32_bf16 v[52:55], v[136:139], v[238:241], v[52:55]
	v_mfma_f32_16x16x32_bf16 v[40:43], v[132:135], v[164:167], v[40:43]
	v_mfma_f32_16x16x32_bf16 v[76:79], v[140:143], v[164:167], v[76:79]
	v_mfma_f32_16x16x32_bf16 v[32:35], v[132:135], v[172:175], v[32:35]
	v_mfma_f32_16x16x32_bf16 v[68:71], v[140:143], v[172:175], v[68:71]
	v_mfma_f32_16x16x32_bf16 v[24:27], v[132:135], v[202:205], v[24:27]
	v_mfma_f32_16x16x32_bf16 v[60:63], v[140:143], v[202:205], v[60:63]
	v_mfma_f32_16x16x32_bf16 v[20:23], v[132:135], v[242:245], v[20:23]
	v_mfma_f32_16x16x32_bf16 v[52:55], v[140:143], v[242:245], v[52:55]
	v_mfma_f32_16x16x32_bf16 v[16:19], v[144:147], v[160:163], v[16:19]
	v_mfma_f32_16x16x32_bf16 v[44:47], v[152:155], v[160:163], v[44:47]
	v_mfma_f32_16x16x32_bf16 v[12:15], v[144:147], v[168:171], v[12:15]
	v_mfma_f32_16x16x32_bf16 v[36:39], v[152:155], v[168:171], v[36:39]
	v_mfma_f32_16x16x32_bf16 v[4:7], v[144:147], v[198:201], v[4:7]
	v_mfma_f32_16x16x32_bf16 v[28:31], v[152:155], v[198:201], v[28:31]
	v_mfma_f32_16x16x32_bf16 v[0:3], v[144:147], v[238:241], v[0:3]
	v_mfma_f32_16x16x32_bf16 v[8:11], v[152:155], v[238:241], v[8:11]
	v_mfma_f32_16x16x32_bf16 v[16:19], v[148:151], v[164:167], v[16:19]
	v_mfma_f32_16x16x32_bf16 v[44:47], v[156:159], v[164:167], v[44:47]
	v_mfma_f32_16x16x32_bf16 v[12:15], v[148:151], v[172:175], v[12:15]
	v_mfma_f32_16x16x32_bf16 v[36:39], v[156:159], v[172:175], v[36:39]
	v_mfma_f32_16x16x32_bf16 v[4:7], v[148:151], v[202:205], v[4:7]
	v_mfma_f32_16x16x32_bf16 v[28:31], v[156:159], v[202:205], v[28:31]
	v_mfma_f32_16x16x32_bf16 v[0:3], v[148:151], v[242:245], v[0:3]
	v_mfma_f32_16x16x32_bf16 v[8:11], v[156:159], v[242:245], v[8:11]
	s_setprio 0
	s_barrier
	s_movk_i32 s2, 0x100
	s_andn2_b64 vcc, exec, s[38:39]
	s_mov_b64 s[84:85], -1
	s_mov_b64 s[38:39], 0
	s_cbranch_vccz .LBB0_42
	s_and_b64 vcc, exec, s[40:41]
	s_cbranch_vccz .LBB0_45
	s_barrier

.LBB0_157:
	v_or_b32_e32 v138, 0x10000, v142
	v_add_u32_e32 v139, 0x10400, v142
	ds_read_b128 v[144:147], v138
	ds_read_b128 v[148:151], v139
	v_add_u32_e32 v138, 0x10800, v142
	v_add_u32_e32 v139, 0x10c00, v142
	ds_read_b128 v[152:155], v138
	ds_read_b128 v[156:159], v139
	v_or_b32_e32 v138, 0x14000, v142
	v_add_u32_e32 v139, 0x14400, v142
	ds_read_b128 v[160:163], v138
	ds_read_b128 v[164:167], v139
	v_add_u32_e32 v138, 0x14800, v142
	v_add_u32_e32 v139, 0x14c00, v142
	ds_read_b128 v[168:171], v138
	ds_read_b128 v[172:175], v139
	s_add_u32 s8, vcc_lo, 0xfffc0080
	s_addc_u32 s9, vcc_hi, -1
	s_cmp_eq_u32 s90, 12
	s_cselect_b32 s11, s5, s9
	s_cselect_b32 s10, s92, s8
	s_cselect_b32 s9, s85, s89
	s_cselect_b32 s8, s96, s88
	s_add_i32 m0, s23, 0xc000
	ds_read_b128 v[186:189], v141
	ds_read_b128 v[190:193], v141 offset:1024
	ds_read_b128 v[194:197], v141 offset:2048
	ds_read_b128 v[198:201], v141 offset:3072
	ds_read_b128 v[202:205], v141 offset:4096
	ds_read_b128 v[220:223], v141 offset:5120
	ds_read_b128 v[224:227], v141 offset:6144
	ds_read_b128 v[228:231], v141 offset:7168
	global_load_lds_dwordx4 v134, vcc
	s_add_i32 m0, s23, 0xe000
	s_nop 0
	global_load_lds_dwordx4 v136, vcc
	s_waitcnt vmcnt(8)
	s_waitcnt lgkmcnt(0)
	s_barrier
	s_setprio 1
	s_waitcnt lgkmcnt(0)
	v_mfma_f32_16x16x32_bf16 v[124:127], v[144:147], v[186:189], v[124:127]
	v_mfma_f32_16x16x32_bf16 v[120:123], v[152:155], v[186:189], v[120:123]
	v_mfma_f32_16x16x32_bf16 v[108:111], v[144:147], v[194:197], v[108:111]
	v_mfma_f32_16x16x32_bf16 v[104:107], v[152:155], v[194:197], v[104:107]
	v_mfma_f32_16x16x32_bf16 v[92:95], v[144:147], v[202:205], v[92:95]
	v_mfma_f32_16x16x32_bf16 v[88:91], v[152:155], v[202:205], v[88:91]
	v_mfma_f32_16x16x32_bf16 v[76:79], v[144:147], v[224:227], v[76:79]
	v_mfma_f32_16x16x32_bf16 v[72:75], v[152:155], v[224:227], v[72:75]
	v_mfma_f32_16x16x32_bf16 v[124:127], v[148:151], v[190:193], v[124:127]
	v_mfma_f32_16x16x32_bf16 v[120:123], v[156:159], v[190:193], v[120:123]
	v_mfma_f32_16x16x32_bf16 v[108:111], v[148:151], v[198:201], v[108:111]
	v_mfma_f32_16x16x32_bf16 v[104:107], v[156:159], v[198:201], v[104:107]
	v_mfma_f32_16x16x32_bf16 v[92:95], v[148:151], v[220:223], v[92:95]
	v_mfma_f32_16x16x32_bf16 v[88:91], v[156:159], v[220:223], v[88:91]
	v_mfma_f32_16x16x32_bf16 v[76:79], v[148:151], v[228:231], v[76:79]
	v_mfma_f32_16x16x32_bf16 v[72:75], v[156:159], v[228:231], v[72:75]
	v_mfma_f32_16x16x32_bf16 v[116:119], v[160:163], v[186:189], v[116:119]
	v_mfma_f32_16x16x32_bf16 v[112:115], v[168:171], v[186:189], v[112:115]
	v_mfma_f32_16x16x32_bf16 v[100:103], v[160:163], v[194:197], v[100:103]
	v_mfma_f32_16x16x32_bf16 v[96:99], v[168:171], v[194:197], v[96:99]
	v_mfma_f32_16x16x32_bf16 v[84:87], v[160:163], v[202:205], v[84:87]
	v_mfma_f32_16x16x32_bf16 v[80:83], v[168:171], v[202:205], v[80:83]
	v_mfma_f32_16x16x32_bf16 v[68:71], v[160:163], v[224:227], v[68:71]
	v_mfma_f32_16x16x32_bf16 v[64:67], v[168:171], v[224:227], v[64:67]
	v_mfma_f32_16x16x32_bf16 v[116:119], v[164:167], v[190:193], v[116:119]
	v_mfma_f32_16x16x32_bf16 v[112:115], v[172:175], v[190:193], v[112:115]
	v_mfma_f32_16x16x32_bf16 v[100:103], v[164:167], v[198:201], v[100:103]
	v_mfma_f32_16x16x32_bf16 v[96:99], v[172:175], v[198:201], v[96:99]
	v_mfma_f32_16x16x32_bf16 v[84:87], v[164:167], v[220:223], v[84:87]
	v_mfma_f32_16x16x32_bf16 v[80:83], v[172:175], v[220:223], v[80:83]
	v_mfma_f32_16x16x32_bf16 v[68:71], v[164:167], v[228:231], v[68:71]
	v_mfma_f32_16x16x32_bf16 v[64:67], v[172:175], v[228:231], v[64:67]
	s_setprio 0
	s_barrier
	s_mov_b32 m0, s25
	v_lshl_add_u64 v[138:139], s[8:9], 0, v[176:177]
	s_add_u32 s60, s8, 0x40000
	ds_read_b128 v[186:189], v141 offset:16384
	ds_read_b128 v[190:193], v141 offset:17408
	ds_read_b128 v[194:197], v141 offset:18432
	ds_read_b128 v[198:201], v141 offset:19456
	ds_read_b128 v[202:205], v141 offset:20480
	ds_read_b128 v[220:223], v141 offset:21504
	ds_read_b128 v[224:227], v141 offset:22528
	ds_read_b128 v[228:231], v141 offset:23552
	global_load_lds_dwordx4 v[138:139], off
	v_lshl_add_u64 v[232:233], s[8:9], 0, v[128:129]
	s_mov_b32 m0, s26
	s_addc_u32 s61, s9, 0
	global_load_lds_dwordx4 v[232:233], off
	s_mov_b32 m0, s27
	v_lshl_add_u64 v[236:237], s[10:11], 0, v[130:131]
	global_load_lds_dwordx4 v176, s[60:61]
	s_mov_b32 m0, s28
	s_nop 0
	global_load_lds_dwordx4 v128, s[60:61]
	v_lshl_add_u64 v[234:235], s[10:11], 0, v[132:133]
	s_mov_b32 m0, s23
	s_nop 0
	global_load_lds_dwordx4 v[234:235], off
	s_mov_b32 m0, s29
	s_nop 0
	global_load_lds_dwordx4 v[236:237], off
	s_waitcnt vmcnt(8)
	s_waitcnt lgkmcnt(0)
	s_barrier
	s_setprio 1
	s_waitcnt lgkmcnt(0)
	v_mfma_f32_16x16x32_bf16 v[60:63], v[144:147], v[186:189], v[60:63]
	v_mfma_f32_16x16x32_bf16 v[56:59], v[152:155], v[186:189], v[56:59]
	v_mfma_f32_16x16x32_bf16 v[44:47], v[144:147], v[194:197], v[44:47]
	v_mfma_f32_16x16x32_bf16 v[40:43], v[152:155], v[194:197], v[40:43]
	v_mfma_f32_16x16x32_bf16 v[28:31], v[144:147], v[202:205], v[28:31]
	v_mfma_f32_16x16x32_bf16 v[24:27], v[152:155], v[202:205], v[24:27]
	v_mfma_f32_16x16x32_bf16 v[12:15], v[144:147], v[224:227], v[12:15]
	v_mfma_f32_16x16x32_bf16 v[8:11], v[152:155], v[224:227], v[8:11]
	v_mfma_f32_16x16x32_bf16 v[60:63], v[148:151], v[190:193], v[60:63]
	v_mfma_f32_16x16x32_bf16 v[56:59], v[156:159], v[190:193], v[56:59]
	v_mfma_f32_16x16x32_bf16 v[44:47], v[148:151], v[198:201], v[44:47]
	v_mfma_f32_16x16x32_bf16 v[40:43], v[156:159], v[198:201], v[40:43]
	v_mfma_f32_16x16x32_bf16 v[28:31], v[148:151], v[220:223], v[28:31]
	v_mfma_f32_16x16x32_bf16 v[24:27], v[156:159], v[220:223], v[24:27]
	v_mfma_f32_16x16x32_bf16 v[12:15], v[148:151], v[228:231], v[12:15]
	v_mfma_f32_16x16x32_bf16 v[8:11], v[156:159], v[228:231], v[8:11]
	v_mfma_f32_16x16x32_bf16 v[52:55], v[160:163], v[186:189], v[52:55]
	v_mfma_f32_16x16x32_bf16 v[48:51], v[168:171], v[186:189], v[48:51]
	v_mfma_f32_16x16x32_bf16 v[36:39], v[160:163], v[194:197], v[36:39]
	v_mfma_f32_16x16x32_bf16 v[32:35], v[168:171], v[194:197], v[32:35]
	v_mfma_f32_16x16x32_bf16 v[20:23], v[160:163], v[202:205], v[20:23]
	v_mfma_f32_16x16x32_bf16 v[16:19], v[168:171], v[202:205], v[16:19]
	v_mfma_f32_16x16x32_bf16 v[4:7], v[160:163], v[224:227], v[4:7]
	v_mfma_f32_16x16x32_bf16 v[0:3], v[168:171], v[224:227], v[0:3]
	v_mfma_f32_16x16x32_bf16 v[52:55], v[164:167], v[190:193], v[52:55]
	v_mfma_f32_16x16x32_bf16 v[48:51], v[172:175], v[190:193], v[48:51]
	v_mfma_f32_16x16x32_bf16 v[36:39], v[164:167], v[198:201], v[36:39]
	v_mfma_f32_16x16x32_bf16 v[32:35], v[172:175], v[198:201], v[32:35]
	v_mfma_f32_16x16x32_bf16 v[20:23], v[164:167], v[220:223], v[20:23]
	v_mfma_f32_16x16x32_bf16 v[16:19], v[172:175], v[220:223], v[16:19]
	v_mfma_f32_16x16x32_bf16 v[4:7], v[164:167], v[228:231], v[4:7]
	v_mfma_f32_16x16x32_bf16 v[0:3], v[172:175], v[228:231], v[0:3]
	s_setprio 0
	s_barrier
	v_or_b32_e32 v144, 0x18000, v142
	v_add_u32_e32 v148, 0x18400, v142
	v_add_u32_e32 v152, 0x18800, v142
	v_add_u32_e32 v156, 0x18c00, v142
	v_or_b32_e32 v160, 0x1c000, v142
	v_add_u32_e32 v164, 0x1c400, v142
	v_add_u32_e32 v168, 0x1c800, v142
	v_add_u32_e32 v172, 0x1cc00, v142
	ds_read_b128 v[144:147], v144
	ds_read_b128 v[148:151], v148
	ds_read_b128 v[152:155], v152
	ds_read_b128 v[156:159], v156
	ds_read_b128 v[160:163], v160
	ds_read_b128 v[164:167], v164
	ds_read_b128 v[168:171], v168
	ds_read_b128 v[172:175], v172
	s_add_u32 s10, s10, 0x40000
	s_addc_u32 s11, s11, 0
	s_mov_b32 m0, s30
	ds_read_b128 v[186:189], v141 offset:32768
	ds_read_b128 v[190:193], v141 offset:33792
	ds_read_b128 v[194:197], v141 offset:34816
	ds_read_b128 v[198:201], v141 offset:35840
	ds_read_b128 v[202:205], v141 offset:36864
	ds_read_b128 v[220:223], v141 offset:37888
	ds_read_b128 v[224:227], v141 offset:38912
	ds_read_b128 v[228:231], v141 offset:39936
	global_load_lds_dwordx4 v132, s[10:11]
	v_lshl_add_u64 v[238:239], s[10:11], 0, v[130:131]
	s_mov_b32 m0, s31
	s_nop 0
	global_load_lds_dwordx4 v[238:239], off
	s_waitcnt vmcnt(8)
	s_waitcnt lgkmcnt(0)
	s_barrier
	s_setprio 1
	s_waitcnt lgkmcnt(0)
	v_mfma_f32_16x16x32_bf16 v[124:127], v[144:147], v[186:189], v[124:127]
	v_mfma_f32_16x16x32_bf16 v[120:123], v[152:155], v[186:189], v[120:123]
	v_mfma_f32_16x16x32_bf16 v[108:111], v[144:147], v[194:197], v[108:111]
	v_mfma_f32_16x16x32_bf16 v[104:107], v[152:155], v[194:197], v[104:107]
	v_mfma_f32_16x16x32_bf16 v[92:95], v[144:147], v[202:205], v[92:95]
	v_mfma_f32_16x16x32_bf16 v[88:91], v[152:155], v[202:205], v[88:91]
	v_mfma_f32_16x16x32_bf16 v[76:79], v[144:147], v[224:227], v[76:79]
	v_mfma_f32_16x16x32_bf16 v[72:75], v[152:155], v[224:227], v[72:75]
	v_mfma_f32_16x16x32_bf16 v[124:127], v[148:151], v[190:193], v[124:127]
	v_mfma_f32_16x16x32_bf16 v[120:123], v[156:159], v[190:193], v[120:123]
	v_mfma_f32_16x16x32_bf16 v[108:111], v[148:151], v[198:201], v[108:111]
	v_mfma_f32_16x16x32_bf16 v[104:107], v[156:159], v[198:201], v[104:107]
	v_mfma_f32_16x16x32_bf16 v[92:95], v[148:151], v[220:223], v[92:95]
	v_mfma_f32_16x16x32_bf16 v[88:91], v[156:159], v[220:223], v[88:91]
	v_mfma_f32_16x16x32_bf16 v[76:79], v[148:151], v[228:231], v[76:79]
	v_mfma_f32_16x16x32_bf16 v[72:75], v[156:159], v[228:231], v[72:75]
	v_mfma_f32_16x16x32_bf16 v[116:119], v[160:163], v[186:189], v[116:119]
	v_mfma_f32_16x16x32_bf16 v[112:115], v[168:171], v[186:189], v[112:115]
	v_mfma_f32_16x16x32_bf16 v[100:103], v[160:163], v[194:197], v[100:103]
	v_mfma_f32_16x16x32_bf16 v[96:99], v[168:171], v[194:197], v[96:99]
	v_mfma_f32_16x16x32_bf16 v[84:87], v[160:163], v[202:205], v[84:87]
	v_mfma_f32_16x16x32_bf16 v[80:83], v[168:171], v[202:205], v[80:83]
	v_mfma_f32_16x16x32_bf16 v[68:71], v[160:163], v[224:227], v[68:71]
	v_mfma_f32_16x16x32_bf16 v[64:67], v[168:171], v[224:227], v[64:67]
	v_mfma_f32_16x16x32_bf16 v[116:119], v[164:167], v[190:193], v[116:119]
	v_mfma_f32_16x16x32_bf16 v[112:115], v[172:175], v[190:193], v[112:115]
	v_mfma_f32_16x16x32_bf16 v[100:103], v[164:167], v[198:201], v[100:103]
	v_mfma_f32_16x16x32_bf16 v[96:99], v[172:175], v[198:201], v[96:99]
	v_mfma_f32_16x16x32_bf16 v[84:87], v[164:167], v[220:223], v[84:87]
	v_mfma_f32_16x16x32_bf16 v[80:83], v[172:175], v[220:223], v[80:83]
	v_mfma_f32_16x16x32_bf16 v[68:71], v[164:167], v[228:231], v[68:71]
	v_mfma_f32_16x16x32_bf16 v[64:67], v[172:175], v[228:231], v[64:67]
	s_setprio 0
	s_barrier
	s_mov_b32 m0, s34
	v_lshl_add_u64 v[138:139], v[138:139], 0, s[0:1]
	s_add_u32 s8, s8, 0x40080
	ds_read_b128 v[186:189], v141 offset:49152
	ds_read_b128 v[190:193], v141 offset:50176
	ds_read_b128 v[194:197], v141 offset:51200
	ds_read_b128 v[198:201], v141 offset:52224
	ds_read_b128 v[202:205], v141 offset:53248
	ds_read_b128 v[220:223], v141 offset:54272
	ds_read_b128 v[224:227], v141 offset:55296
	ds_read_b128 v[228:231], v141 offset:56320
	global_load_lds_dwordx4 v[138:139], off
	v_lshl_add_u64 v[138:139], v[232:233], 0, s[0:1]
	s_mov_b32 m0, s35
	s_addc_u32 s9, s9, 0
	global_load_lds_dwordx4 v[138:139], off
	s_mov_b32 m0, s74
	s_nop 0
	global_load_lds_dwordx4 v176, s[8:9]
	s_mov_b32 m0, s75
	s_nop 0
	global_load_lds_dwordx4 v128, s[8:9]
	v_lshl_add_u64 v[138:139], v[234:235], 0, s[0:1]
	s_mov_b32 m0, s42
	s_nop 0
	global_load_lds_dwordx4 v[138:139], off
	v_lshl_add_u64 v[138:139], v[236:237], 0, s[0:1]
	s_mov_b32 m0, s43
	s_nop 0
	global_load_lds_dwordx4 v[138:139], off
	s_waitcnt vmcnt(8)
	s_waitcnt lgkmcnt(0)
	s_barrier
	s_setprio 1
	s_waitcnt lgkmcnt(0)
	v_mfma_f32_16x16x32_bf16 v[60:63], v[144:147], v[186:189], v[60:63]
	v_mfma_f32_16x16x32_bf16 v[56:59], v[152:155], v[186:189], v[56:59]
	v_mfma_f32_16x16x32_bf16 v[44:47], v[144:147], v[194:197], v[44:47]
	v_mfma_f32_16x16x32_bf16 v[40:43], v[152:155], v[194:197], v[40:43]
	v_mfma_f32_16x16x32_bf16 v[28:31], v[144:147], v[202:205], v[28:31]
	v_mfma_f32_16x16x32_bf16 v[24:27], v[152:155], v[202:205], v[24:27]
	v_mfma_f32_16x16x32_bf16 v[12:15], v[144:147], v[224:227], v[12:15]
	v_mfma_f32_16x16x32_bf16 v[8:11], v[152:155], v[224:227], v[8:11]
	v_mfma_f32_16x16x32_bf16 v[60:63], v[148:151], v[190:193], v[60:63]
	v_mfma_f32_16x16x32_bf16 v[56:59], v[156:159], v[190:193], v[56:59]
	v_mfma_f32_16x16x32_bf16 v[44:47], v[148:151], v[198:201], v[44:47]
	v_mfma_f32_16x16x32_bf16 v[40:43], v[156:159], v[198:201], v[40:43]
	v_mfma_f32_16x16x32_bf16 v[28:31], v[148:151], v[220:223], v[28:31]
	v_mfma_f32_16x16x32_bf16 v[24:27], v[156:159], v[220:223], v[24:27]
	v_mfma_f32_16x16x32_bf16 v[12:15], v[148:151], v[228:231], v[12:15]
	v_mfma_f32_16x16x32_bf16 v[8:11], v[156:159], v[228:231], v[8:11]
	v_mfma_f32_16x16x32_bf16 v[52:55], v[160:163], v[186:189], v[52:55]
	v_mfma_f32_16x16x32_bf16 v[48:51], v[168:171], v[186:189], v[48:51]
	v_mfma_f32_16x16x32_bf16 v[36:39], v[160:163], v[194:197], v[36:39]
	v_mfma_f32_16x16x32_bf16 v[32:35], v[168:171], v[194:197], v[32:35]
	v_mfma_f32_16x16x32_bf16 v[20:23], v[160:163], v[202:205], v[20:23]
	v_mfma_f32_16x16x32_bf16 v[16:19], v[168:171], v[202:205], v[16:19]
	v_mfma_f32_16x16x32_bf16 v[4:7], v[160:163], v[224:227], v[4:7]
	v_mfma_f32_16x16x32_bf16 v[0:3], v[168:171], v[224:227], v[0:3]
	v_mfma_f32_16x16x32_bf16 v[52:55], v[164:167], v[190:193], v[52:55]
	v_mfma_f32_16x16x32_bf16 v[48:51], v[172:175], v[190:193], v[48:51]
	v_mfma_f32_16x16x32_bf16 v[36:39], v[164:167], v[198:201], v[36:39]
	v_mfma_f32_16x16x32_bf16 v[32:35], v[172:175], v[198:201], v[32:35]
	v_mfma_f32_16x16x32_bf16 v[20:23], v[164:167], v[220:223], v[20:23]
	v_mfma_f32_16x16x32_bf16 v[16:19], v[172:175], v[220:223], v[16:19]
	v_mfma_f32_16x16x32_bf16 v[4:7], v[164:167], v[228:231], v[4:7]
	v_mfma_f32_16x16x32_bf16 v[0:3], v[172:175], v[228:231], v[0:3]
	s_setprio 0
	s_barrier
	s_add_i32 s90, s90, 2
	s_add_u32 vcc_lo, vcc_lo, 0x100
	s_addc_u32 vcc_hi, vcc_hi, 0
	s_add_u32 s88, s88, 0x100
	s_addc_u32 s89, s89, 0
	s_cmp_gt_u32 s90, 13
	s_cbranch_scc0 .LBB0_157
	s_and_b64 vcc, exec, s[40:41]
	s_cbranch_vccz .LBB0_160
	s_barrier

.LBB0_326:
	v_or_b32_e32 v13, 0x10000, v12
	v_add_u32_e32 v18, 0x10400, v12
	ds_read_b128 v[14:17], v13
	ds_read_b128 v[18:21], v18
	v_add_u32_e32 v13, 0x10800, v12
	v_add_u32_e32 v26, 0x10c00, v12
	s_add_u32 s2, s40, s90
	ds_read_b128 v[22:25], v13
	ds_read_b128 v[26:29], v26
	v_or_b32_e32 v13, 0x14000, v12
	s_addc_u32 s3, s41, s91
	v_add_u32_e32 v30, 0x14400, v12
	ds_read_b128 v[160:163], v13
	ds_read_b128 v[164:167], v30
	v_add_u32_e32 v13, 0x14800, v12
	s_add_u32 s2, s2, 0x100
	v_add_u32_e32 v30, 0x14c00, v12
	ds_read_b128 v[168:171], v13
	ds_read_b128 v[172:175], v30
	s_addc_u32 s3, s3, 0
	s_add_u32 s60, s75, s90
	s_addc_u32 s61, s83, s91
	s_cmpk_eq_i32 s90, 0x700
	s_cselect_b32 s7, s85, s3
	s_cselect_b32 s6, s92, s2
	s_cselect_b32 s3, s5, s61
	s_cselect_b32 s2, s94, s60
	v_lshl_add_u64 v[30:31], v[6:7], 0, s[90:91]
	s_add_i32 m0, s22, 0xc000
	ds_read_b128 v[186:189], v11
	ds_read_b128 v[194:197], v11 offset:1024
	ds_read_b128 v[198:201], v11 offset:2048
	ds_read_b128 v[202:205], v11 offset:3072
	ds_read_b128 v[220:223], v11 offset:4096
	ds_read_b128 v[224:227], v11 offset:5120
	ds_read_b128 v[228:231], v11 offset:6144
	ds_read_b128 v[232:235], v11 offset:7168
	global_load_lds_dwordx4 v[30:31], off
	v_lshl_add_u64 v[30:31], v[8:9], 0, s[90:91]
	s_add_i32 m0, s22, 0xe000
	s_nop 0
	global_load_lds_dwordx4 v[30:31], off
	s_waitcnt vmcnt(8)
	s_waitcnt lgkmcnt(0)
	s_barrier
	s_setprio 1
	s_waitcnt lgkmcnt(0)
	v_mfma_f32_16x16x32_bf16 v[156:159], v[14:17], v[186:189], v[156:159]
	v_mfma_f32_16x16x32_bf16 v[152:155], v[22:25], v[186:189], v[152:155]
	v_mfma_f32_16x16x32_bf16 v[140:143], v[14:17], v[198:201], v[140:143]
	v_mfma_f32_16x16x32_bf16 v[136:139], v[22:25], v[198:201], v[136:139]
	v_mfma_f32_16x16x32_bf16 v[124:127], v[14:17], v[220:223], v[124:127]
	v_mfma_f32_16x16x32_bf16 v[120:123], v[22:25], v[220:223], v[120:123]
	v_mfma_f32_16x16x32_bf16 v[108:111], v[14:17], v[228:231], v[108:111]
	v_mfma_f32_16x16x32_bf16 v[104:107], v[22:25], v[228:231], v[104:107]
	v_mfma_f32_16x16x32_bf16 v[156:159], v[18:21], v[194:197], v[156:159]
	v_mfma_f32_16x16x32_bf16 v[152:155], v[26:29], v[194:197], v[152:155]
	v_mfma_f32_16x16x32_bf16 v[140:143], v[18:21], v[202:205], v[140:143]
	v_mfma_f32_16x16x32_bf16 v[136:139], v[26:29], v[202:205], v[136:139]
	v_mfma_f32_16x16x32_bf16 v[124:127], v[18:21], v[224:227], v[124:127]
	v_mfma_f32_16x16x32_bf16 v[120:123], v[26:29], v[224:227], v[120:123]
	v_mfma_f32_16x16x32_bf16 v[108:111], v[18:21], v[232:235], v[108:111]
	v_mfma_f32_16x16x32_bf16 v[104:107], v[26:29], v[232:235], v[104:107]
	v_mfma_f32_16x16x32_bf16 v[148:151], v[160:163], v[186:189], v[148:151]
	v_mfma_f32_16x16x32_bf16 v[144:147], v[168:171], v[186:189], v[144:147]
	v_mfma_f32_16x16x32_bf16 v[132:135], v[160:163], v[198:201], v[132:135]
	v_mfma_f32_16x16x32_bf16 v[128:131], v[168:171], v[198:201], v[128:131]
	v_mfma_f32_16x16x32_bf16 v[116:119], v[160:163], v[220:223], v[116:119]
	v_mfma_f32_16x16x32_bf16 v[112:115], v[168:171], v[220:223], v[112:115]
	v_mfma_f32_16x16x32_bf16 v[100:103], v[160:163], v[228:231], v[100:103]
	v_mfma_f32_16x16x32_bf16 v[96:99], v[168:171], v[228:231], v[96:99]
	v_mfma_f32_16x16x32_bf16 v[148:151], v[164:167], v[194:197], v[148:151]
	v_mfma_f32_16x16x32_bf16 v[144:147], v[172:175], v[194:197], v[144:147]
	v_mfma_f32_16x16x32_bf16 v[132:135], v[164:167], v[202:205], v[132:135]
	v_mfma_f32_16x16x32_bf16 v[128:131], v[172:175], v[202:205], v[128:131]
	v_mfma_f32_16x16x32_bf16 v[116:119], v[164:167], v[224:227], v[116:119]
	v_mfma_f32_16x16x32_bf16 v[112:115], v[172:175], v[224:227], v[112:115]
	v_mfma_f32_16x16x32_bf16 v[100:103], v[164:167], v[232:235], v[100:103]
	v_mfma_f32_16x16x32_bf16 v[96:99], v[172:175], v[232:235], v[96:99]
	s_setprio 0
	s_barrier
	s_mov_b32 m0, s23
	v_lshl_add_u64 v[190:191], s[2:3], 0, v[176:177]
	s_add_u32 s60, s2, 0x40000
	ds_read_b128 v[186:189], v11 offset:16384
	ds_read_b128 v[194:197], v11 offset:17408
	ds_read_b128 v[198:201], v11 offset:18432
	ds_read_b128 v[202:205], v11 offset:19456
	ds_read_b128 v[220:223], v11 offset:20480
	ds_read_b128 v[224:227], v11 offset:21504
	ds_read_b128 v[228:231], v11 offset:22528
	ds_read_b128 v[232:235], v11 offset:23552
	global_load_lds_dwordx4 v[190:191], off
	v_lshl_add_u64 v[214:215], s[2:3], 0, v[0:1]
	s_mov_b32 m0, s24
	s_addc_u32 s61, s3, 0
	global_load_lds_dwordx4 v[214:215], off
	s_mov_b32 m0, s25
	v_lshl_add_u64 v[236:237], s[6:7], 0, v[176:177]
	global_load_lds_dwordx4 v176, s[60:61]
	s_mov_b32 m0, s26
	v_lshl_add_u64 v[238:239], s[6:7], 0, v[0:1]
	global_load_lds_dwordx4 v0, s[60:61]
	s_mov_b32 m0, s22
	s_nop 0
	global_load_lds_dwordx4 v[236:237], off
	s_mov_b32 m0, s27
	s_nop 0
	global_load_lds_dwordx4 v[238:239], off
	s_waitcnt vmcnt(8)
	s_waitcnt lgkmcnt(0)
	s_barrier
	s_setprio 1
	s_waitcnt lgkmcnt(0)
	v_mfma_f32_16x16x32_bf16 v[92:95], v[14:17], v[186:189], v[92:95]
	v_mfma_f32_16x16x32_bf16 v[88:91], v[22:25], v[186:189], v[88:91]
	v_mfma_f32_16x16x32_bf16 v[76:79], v[14:17], v[198:201], v[76:79]
	v_mfma_f32_16x16x32_bf16 v[72:75], v[22:25], v[198:201], v[72:75]
	v_mfma_f32_16x16x32_bf16 v[60:63], v[14:17], v[220:223], v[60:63]
	v_mfma_f32_16x16x32_bf16 v[56:59], v[22:25], v[220:223], v[56:59]
	v_mfma_f32_16x16x32_bf16 v[14:17], v[14:17], v[228:231], v[44:47]
	v_mfma_f32_16x16x32_bf16 v[92:95], v[18:21], v[194:197], v[92:95]
	v_mfma_f32_16x16x32_bf16 v[88:91], v[26:29], v[194:197], v[88:91]
	v_mfma_f32_16x16x32_bf16 v[76:79], v[18:21], v[202:205], v[76:79]
	v_mfma_f32_16x16x32_bf16 v[72:75], v[26:29], v[202:205], v[72:75]
	v_mfma_f32_16x16x32_bf16 v[60:63], v[18:21], v[224:227], v[60:63]
	v_mfma_f32_16x16x32_bf16 v[56:59], v[26:29], v[224:227], v[56:59]
	v_mfma_f32_16x16x32_bf16 v[14:17], v[18:21], v[232:235], v[14:17]
	v_mfma_f32_16x16x32_bf16 v[18:21], v[22:25], v[228:231], v[40:43]
	v_mfma_f32_16x16x32_bf16 v[18:21], v[26:29], v[232:235], v[18:21]
	v_mfma_f32_16x16x32_bf16 v[40:43], v[160:163], v[198:201], v[68:71]
	v_mfma_f32_16x16x32_bf16 v[68:71], v[164:167], v[202:205], v[40:43]
	v_mfma_f32_16x16x32_bf16 v[40:43], v[168:171], v[198:201], v[64:67]
	v_mfma_f32_16x16x32_bf16 v[64:67], v[172:175], v[202:205], v[40:43]
	v_mfma_f32_16x16x32_bf16 v[40:43], v[160:163], v[220:223], v[52:55]
	v_mfma_f32_16x16x32_bf16 v[52:55], v[164:167], v[224:227], v[40:43]
	v_mfma_f32_16x16x32_bf16 v[40:43], v[168:171], v[220:223], v[48:51]
	v_mfma_f32_16x16x32_bf16 v[36:39], v[160:163], v[228:231], v[36:39]
	v_mfma_f32_16x16x32_bf16 v[30:33], v[168:171], v[228:231], v[32:35]
	v_mfma_f32_16x16x32_bf16 v[22:25], v[160:163], v[186:189], v[84:87]
	v_mfma_f32_16x16x32_bf16 v[26:29], v[168:171], v[186:189], v[80:83]
	v_mfma_f32_16x16x32_bf16 v[48:51], v[172:175], v[224:227], v[40:43]
	v_mfma_f32_16x16x32_bf16 v[36:39], v[164:167], v[232:235], v[36:39]
	v_mfma_f32_16x16x32_bf16 v[30:33], v[172:175], v[232:235], v[30:33]
	v_mfma_f32_16x16x32_bf16 v[22:25], v[164:167], v[194:197], v[22:25]
	v_mfma_f32_16x16x32_bf16 v[26:29], v[172:175], v[194:197], v[26:29]
	s_setprio 0
	s_barrier
	v_or_b32_e32 v13, 0x18000, v12
	v_add_u32_e32 v34, 0x18400, v12
	ds_read_b128 v[40:43], v13
	ds_read_b128 v[44:47], v34
	v_add_u32_e32 v13, 0x18800, v12
	v_add_u32_e32 v34, 0x18c00, v12
	ds_read_b128 v[80:83], v13
	ds_read_b128 v[84:87], v34
	v_or_b32_e32 v13, 0x1c000, v12
	v_add_u32_e32 v34, 0x1c400, v12
	ds_read_b128 v[160:163], v13
	ds_read_b128 v[164:167], v34
	v_add_u32_e32 v13, 0x1c800, v12
	v_add_u32_e32 v34, 0x1cc00, v12
	ds_read_b128 v[168:171], v13
	ds_read_b128 v[172:175], v34
	s_add_u32 s6, s6, 0x40000
	s_addc_u32 s7, s7, 0
	s_mov_b32 m0, s28
	ds_read_b128 v[186:189], v11 offset:32768
	ds_read_b128 v[194:197], v11 offset:33792
	ds_read_b128 v[198:201], v11 offset:34816
	ds_read_b128 v[202:205], v11 offset:35840
	ds_read_b128 v[220:223], v11 offset:36864
	ds_read_b128 v[224:227], v11 offset:37888
	ds_read_b128 v[228:231], v11 offset:38912
	ds_read_b128 v[232:235], v11 offset:39936
	global_load_lds_dwordx4 v176, s[6:7]
	s_mov_b32 m0, s29
	s_nop 0
	global_load_lds_dwordx4 v0, s[6:7]
	s_waitcnt vmcnt(8)
	s_waitcnt lgkmcnt(0)
	s_barrier
	s_setprio 1
	s_waitcnt lgkmcnt(0)
	v_mfma_f32_16x16x32_bf16 v[156:159], v[40:43], v[186:189], v[156:159]
	v_mfma_f32_16x16x32_bf16 v[152:155], v[80:83], v[186:189], v[152:155]
	v_mfma_f32_16x16x32_bf16 v[140:143], v[40:43], v[198:201], v[140:143]
	v_mfma_f32_16x16x32_bf16 v[136:139], v[80:83], v[198:201], v[136:139]
	v_mfma_f32_16x16x32_bf16 v[124:127], v[40:43], v[220:223], v[124:127]
	v_mfma_f32_16x16x32_bf16 v[120:123], v[80:83], v[220:223], v[120:123]
	v_mfma_f32_16x16x32_bf16 v[108:111], v[40:43], v[228:231], v[108:111]
	v_mfma_f32_16x16x32_bf16 v[104:107], v[80:83], v[228:231], v[104:107]
	v_mfma_f32_16x16x32_bf16 v[156:159], v[44:47], v[194:197], v[156:159]
	v_mfma_f32_16x16x32_bf16 v[152:155], v[84:87], v[194:197], v[152:155]
	v_mfma_f32_16x16x32_bf16 v[140:143], v[44:47], v[202:205], v[140:143]
	v_mfma_f32_16x16x32_bf16 v[136:139], v[84:87], v[202:205], v[136:139]
	v_mfma_f32_16x16x32_bf16 v[124:127], v[44:47], v[224:227], v[124:127]
	v_mfma_f32_16x16x32_bf16 v[120:123], v[84:87], v[224:227], v[120:123]
	v_mfma_f32_16x16x32_bf16 v[108:111], v[44:47], v[232:235], v[108:111]
	v_mfma_f32_16x16x32_bf16 v[104:107], v[84:87], v[232:235], v[104:107]
	v_mfma_f32_16x16x32_bf16 v[148:151], v[160:163], v[186:189], v[148:151]
	v_mfma_f32_16x16x32_bf16 v[144:147], v[168:171], v[186:189], v[144:147]
	v_mfma_f32_16x16x32_bf16 v[132:135], v[160:163], v[198:201], v[132:135]
	v_mfma_f32_16x16x32_bf16 v[128:131], v[168:171], v[198:201], v[128:131]
	v_mfma_f32_16x16x32_bf16 v[116:119], v[160:163], v[220:223], v[116:119]
	v_mfma_f32_16x16x32_bf16 v[112:115], v[168:171], v[220:223], v[112:115]
	v_mfma_f32_16x16x32_bf16 v[100:103], v[160:163], v[228:231], v[100:103]
	v_mfma_f32_16x16x32_bf16 v[96:99], v[168:171], v[228:231], v[96:99]
	v_mfma_f32_16x16x32_bf16 v[148:151], v[164:167], v[194:197], v[148:151]
	v_mfma_f32_16x16x32_bf16 v[144:147], v[172:175], v[194:197], v[144:147]
	v_mfma_f32_16x16x32_bf16 v[132:135], v[164:167], v[202:205], v[132:135]
	v_mfma_f32_16x16x32_bf16 v[128:131], v[172:175], v[202:205], v[128:131]
	v_mfma_f32_16x16x32_bf16 v[116:119], v[164:167], v[224:227], v[116:119]
	v_mfma_f32_16x16x32_bf16 v[112:115], v[172:175], v[224:227], v[112:115]
	v_mfma_f32_16x16x32_bf16 v[100:103], v[164:167], v[232:235], v[100:103]
	v_mfma_f32_16x16x32_bf16 v[96:99], v[172:175], v[232:235], v[96:99]
	s_setprio 0
	s_barrier
	s_mov_b32 m0, s30
	v_lshl_add_u64 v[34:35], v[190:191], 0, s[0:1]
	s_add_u32 s2, s2, 0x40080
	ds_read_b128 v[186:189], v11 offset:49152
	ds_read_b128 v[194:197], v11 offset:50176
	ds_read_b128 v[198:201], v11 offset:51200
	ds_read_b128 v[202:205], v11 offset:52224
	ds_read_b128 v[220:223], v11 offset:53248
	ds_read_b128 v[224:227], v11 offset:54272
	ds_read_b128 v[228:231], v11 offset:55296
	ds_read_b128 v[232:235], v11 offset:56320
	global_load_lds_dwordx4 v[34:35], off
	v_lshl_add_u64 v[34:35], v[214:215], 0, s[0:1]
	s_mov_b32 m0, s31
	s_addc_u32 s3, s3, 0
	global_load_lds_dwordx4 v[34:35], off
	s_mov_b32 m0, s42
	s_nop 0
	global_load_lds_dwordx4 v176, s[2:3]
	s_mov_b32 m0, s43
	s_nop 0
	global_load_lds_dwordx4 v0, s[2:3]
	v_lshl_add_u64 v[34:35], v[236:237], 0, s[0:1]
	s_mov_b32 m0, s34
	s_nop 0
	global_load_lds_dwordx4 v[34:35], off
	v_lshl_add_u64 v[34:35], v[238:239], 0, s[0:1]
	s_mov_b32 m0, s35
	s_nop 0
	global_load_lds_dwordx4 v[34:35], off
	s_waitcnt vmcnt(8)
	s_waitcnt lgkmcnt(0)
	s_barrier
	s_setprio 1
	s_waitcnt lgkmcnt(0)
	v_mfma_f32_16x16x32_bf16 v[92:95], v[40:43], v[186:189], v[92:95]
	v_mfma_f32_16x16x32_bf16 v[76:79], v[40:43], v[198:201], v[76:79]
	v_mfma_f32_16x16x32_bf16 v[60:63], v[40:43], v[220:223], v[60:63]
	v_mfma_f32_16x16x32_bf16 v[14:17], v[40:43], v[228:231], v[14:17]
	v_mfma_f32_16x16x32_bf16 v[92:95], v[44:47], v[194:197], v[92:95]
	v_mfma_f32_16x16x32_bf16 v[88:91], v[80:83], v[186:189], v[88:91]
	v_mfma_f32_16x16x32_bf16 v[76:79], v[44:47], v[202:205], v[76:79]
	v_mfma_f32_16x16x32_bf16 v[72:75], v[80:83], v[198:201], v[72:75]
	v_mfma_f32_16x16x32_bf16 v[60:63], v[44:47], v[224:227], v[60:63]
	v_mfma_f32_16x16x32_bf16 v[56:59], v[80:83], v[220:223], v[56:59]
	v_mfma_f32_16x16x32_bf16 v[44:47], v[44:47], v[232:235], v[14:17]
	v_mfma_f32_16x16x32_bf16 v[14:17], v[80:83], v[228:231], v[18:21]
	v_mfma_f32_16x16x32_bf16 v[88:91], v[84:87], v[194:197], v[88:91]
	v_mfma_f32_16x16x32_bf16 v[72:75], v[84:87], v[202:205], v[72:75]
	v_mfma_f32_16x16x32_bf16 v[56:59], v[84:87], v[224:227], v[56:59]
	v_mfma_f32_16x16x32_bf16 v[40:43], v[84:87], v[232:235], v[14:17]
	v_mfma_f32_16x16x32_bf16 v[14:17], v[160:163], v[186:189], v[22:25]
	v_mfma_f32_16x16x32_bf16 v[84:87], v[164:167], v[194:197], v[14:17]
	v_mfma_f32_16x16x32_bf16 v[14:17], v[168:171], v[186:189], v[26:29]
	v_mfma_f32_16x16x32_bf16 v[80:83], v[172:175], v[194:197], v[14:17]
	v_mfma_f32_16x16x32_bf16 v[14:17], v[160:163], v[198:201], v[68:71]
	v_mfma_f32_16x16x32_bf16 v[68:71], v[164:167], v[202:205], v[14:17]
	v_mfma_f32_16x16x32_bf16 v[14:17], v[168:171], v[198:201], v[64:67]
	v_mfma_f32_16x16x32_bf16 v[64:67], v[172:175], v[202:205], v[14:17]
	v_mfma_f32_16x16x32_bf16 v[14:17], v[160:163], v[220:223], v[52:55]
	v_mfma_f32_16x16x32_bf16 v[52:55], v[164:167], v[224:227], v[14:17]
	v_mfma_f32_16x16x32_bf16 v[14:17], v[168:171], v[220:223], v[48:51]
	v_mfma_f32_16x16x32_bf16 v[48:51], v[172:175], v[224:227], v[14:17]
	v_mfma_f32_16x16x32_bf16 v[14:17], v[160:163], v[228:231], v[36:39]
	v_mfma_f32_16x16x32_bf16 v[36:39], v[164:167], v[232:235], v[14:17]
	v_mfma_f32_16x16x32_bf16 v[14:17], v[168:171], v[228:231], v[30:33]
	v_mfma_f32_16x16x32_bf16 v[32:35], v[172:175], v[232:235], v[14:17]
	s_setprio 0
	s_barrier
	s_add_i32 s95, s95, 2
	s_add_u32 s90, s90, 0x100
	s_addc_u32 s91, s91, 0
	s_cmp_gt_u32 s95, 13
	s_cbranch_scc0 .LBB0_326
	s_add_u32 s2, s75, 0xffffff00
	s_addc_u32 s3, s83, -1
	s_andn2_b64 vcc, exec, s[38:39]
	s_cbranch_vccnz .LBB0_317
	v_mov_b32_e32 v32, 0
	s_mov_b32 s9, s4
	s_mov_b32 s82, s84
	s_mov_b64 s[40:41], s[88:89]
	s_mov_b32 s72, s74
	v_mov_b32_e32 v33, v32
	v_mov_b32_e32 v34, v32
	v_mov_b32_e32 v35, v32
	v_mov_b32_e32 v36, v32
	v_mov_b32_e32 v37, v32
	v_mov_b32_e32 v38, v32
	v_mov_b32_e32 v39, v32
	v_mov_b32_e32 v48, v32
	v_mov_b32_e32 v49, v32
	v_mov_b32_e32 v50, v32
	v_mov_b32_e32 v51, v32
	v_mov_b32_e32 v52, v32
	v_mov_b32_e32 v53, v32
	v_mov_b32_e32 v54, v32
	v_mov_b32_e32 v55, v32
	v_mov_b32_e32 v64, v32
	v_mov_b32_e32 v65, v32
	v_mov_b32_e32 v66, v32
	v_mov_b32_e32 v67, v32
	v_mov_b32_e32 v68, v32
	v_mov_b32_e32 v69, v32
	v_mov_b32_e32 v70, v32
	v_mov_b32_e32 v71, v32
	v_mov_b32_e32 v80, v32
	v_mov_b32_e32 v81, v32
	v_mov_b32_e32 v82, v32
	v_mov_b32_e32 v83, v32
	v_mov_b32_e32 v84, v32
	v_mov_b32_e32 v85, v32
	v_mov_b32_e32 v86, v32
	v_mov_b32_e32 v87, v32
	v_mov_b32_e32 v40, v32
	v_mov_b32_e32 v41, v32
	v_mov_b32_e32 v42, v32
	v_mov_b32_e32 v43, v32
	v_mov_b32_e32 v44, v32
	v_mov_b32_e32 v45, v32
	v_mov_b32_e32 v46, v32
	v_mov_b32_e32 v47, v32
	v_mov_b32_e32 v56, v32
	v_mov_b32_e32 v57, v32
	v_mov_b32_e32 v58, v32
	v_mov_b32_e32 v59, v32
	v_mov_b32_e32 v60, v32
	v_mov_b32_e32 v61, v32
	v_mov_b32_e32 v62, v32
	v_mov_b32_e32 v63, v32
	v_mov_b32_e32 v72, v32
	v_mov_b32_e32 v73, v32
	v_mov_b32_e32 v74, v32
	v_mov_b32_e32 v75, v32
	v_mov_b32_e32 v76, v32
	v_mov_b32_e32 v77, v32
	v_mov_b32_e32 v78, v32
	v_mov_b32_e32 v79, v32
	v_mov_b32_e32 v88, v32
	v_mov_b32_e32 v89, v32
	v_mov_b32_e32 v90, v32
	v_mov_b32_e32 v91, v32
	v_mov_b32_e32 v92, v32
	v_mov_b32_e32 v93, v32
	v_mov_b32_e32 v94, v32
	v_mov_b32_e32 v95, v32
	v_mov_b32_e32 v96, v32
	v_mov_b32_e32 v97, v32
	v_mov_b32_e32 v98, v32
	v_mov_b32_e32 v99, v32
	v_mov_b32_e32 v100, v32
	v_mov_b32_e32 v101, v32
	v_mov_b32_e32 v102, v32
	v_mov_b32_e32 v103, v32
	v_mov_b32_e32 v112, v32
	v_mov_b32_e32 v113, v32
	v_mov_b32_e32 v114, v32
	v_mov_b32_e32 v115, v32
	v_mov_b32_e32 v116, v32
	v_mov_b32_e32 v117, v32
	v_mov_b32_e32 v118, v32
	v_mov_b32_e32 v119, v32
	v_mov_b32_e32 v128, v32
	v_mov_b32_e32 v129, v32
	v_mov_b32_e32 v130, v32
	v_mov_b32_e32 v131, v32
	v_mov_b32_e32 v132, v32
	v_mov_b32_e32 v133, v32
	v_mov_b32_e32 v134, v32
	v_mov_b32_e32 v135, v32
	v_mov_b32_e32 v144, v32
	v_mov_b32_e32 v145, v32
	v_mov_b32_e32 v146, v32
	v_mov_b32_e32 v147, v32
	v_mov_b32_e32 v148, v32
	v_mov_b32_e32 v149, v32
	v_mov_b32_e32 v150, v32
	v_mov_b32_e32 v151, v32
	v_mov_b32_e32 v104, v32
	v_mov_b32_e32 v105, v32
	v_mov_b32_e32 v106, v32
	v_mov_b32_e32 v107, v32
	v_mov_b32_e32 v108, v32
	v_mov_b32_e32 v109, v32
	v_mov_b32_e32 v110, v32
	v_mov_b32_e32 v111, v32
	v_mov_b32_e32 v120, v32
	v_mov_b32_e32 v121, v32
	v_mov_b32_e32 v122, v32
	v_mov_b32_e32 v123, v32
	v_mov_b32_e32 v124, v32
	v_mov_b32_e32 v125, v32
	v_mov_b32_e32 v126, v32
	v_mov_b32_e32 v127, v32
	v_mov_b32_e32 v136, v32
	v_mov_b32_e32 v137, v32
	v_mov_b32_e32 v138, v32
	v_mov_b32_e32 v139, v32
	v_mov_b32_e32 v140, v32
	v_mov_b32_e32 v141, v32
	v_mov_b32_e32 v142, v32
	v_mov_b32_e32 v143, v32
	v_mov_b32_e32 v152, v32
	v_mov_b32_e32 v153, v32
	v_mov_b32_e32 v154, v32
	v_mov_b32_e32 v155, v32
	v_mov_b32_e32 v156, v32
	v_mov_b32_e32 v157, v32
	v_mov_b32_e32 v158, v32
	v_mov_b32_e32 v159, v32
	s_andn2_b64 vcc, exec, s[36:37]
	s_cbranch_vccnz .LBB0_318

.LBB0_438:
	v_or_b32_e32 v143, 0x10000, v140
	v_add_u32_e32 v148, 0x10400, v140
	ds_read_b128 v[144:147], v143
	ds_read_b128 v[148:151], v148
	v_add_u32_e32 v143, 0x10800, v140
	v_add_u32_e32 v156, 0x10c00, v140
	ds_read_b128 v[152:155], v143
	ds_read_b128 v[156:159], v156
	v_or_b32_e32 v143, 0x14000, v140
	v_add_u32_e32 v164, 0x14400, v140
	ds_read_b128 v[160:163], v143
	ds_read_b128 v[164:167], v164
	v_add_u32_e32 v143, 0x14800, v140
	v_add_u32_e32 v172, 0x14c00, v140
	ds_read_b128 v[168:171], v143
	ds_read_b128 v[172:175], v172
	s_add_u32 s2, s90, 0xfffc0080
	s_addc_u32 s3, s91, -1
	s_cmp_eq_u32 s95, 12
	s_cselect_b32 s7, s8, s3
	s_cselect_b32 s6, s9, s2
	s_cselect_b32 s3, s83, s94
	s_cselect_b32 s2, s85, s92
	s_add_i32 m0, s20, 0xc000
	ds_read_b128 v[186:189], v139
	ds_read_b128 v[190:193], v139 offset:1024
	ds_read_b128 v[194:197], v139 offset:2048
	ds_read_b128 v[198:201], v139 offset:3072
	ds_read_b128 v[202:205], v139 offset:4096
	ds_read_b128 v[220:223], v139 offset:5120
	ds_read_b128 v[224:227], v139 offset:6144
	ds_read_b128 v[228:231], v139 offset:7168
	global_load_lds_dwordx4 v134, s[90:91]
	s_add_i32 m0, s20, 0xe000
	s_nop 0
	global_load_lds_dwordx4 v136, s[90:91]
	s_waitcnt vmcnt(8)
	s_waitcnt lgkmcnt(0)
	s_barrier
	s_setprio 1
	s_waitcnt lgkmcnt(0)
	v_mfma_f32_16x16x32_bf16 v[124:127], v[144:147], v[186:189], v[124:127]
	v_mfma_f32_16x16x32_bf16 v[120:123], v[152:155], v[186:189], v[120:123]
	v_mfma_f32_16x16x32_bf16 v[116:119], v[144:147], v[194:197], v[116:119]
	v_mfma_f32_16x16x32_bf16 v[112:115], v[152:155], v[194:197], v[112:115]
	v_mfma_f32_16x16x32_bf16 v[100:103], v[144:147], v[202:205], v[100:103]
	v_mfma_f32_16x16x32_bf16 v[96:99], v[152:155], v[202:205], v[96:99]
	v_mfma_f32_16x16x32_bf16 v[84:87], v[144:147], v[224:227], v[84:87]
	v_mfma_f32_16x16x32_bf16 v[80:83], v[152:155], v[224:227], v[80:83]
	v_mfma_f32_16x16x32_bf16 v[124:127], v[148:151], v[190:193], v[124:127]
	v_mfma_f32_16x16x32_bf16 v[120:123], v[156:159], v[190:193], v[120:123]
	v_mfma_f32_16x16x32_bf16 v[116:119], v[148:151], v[198:201], v[116:119]
	v_mfma_f32_16x16x32_bf16 v[112:115], v[156:159], v[198:201], v[112:115]
	v_mfma_f32_16x16x32_bf16 v[100:103], v[148:151], v[220:223], v[100:103]
	v_mfma_f32_16x16x32_bf16 v[96:99], v[156:159], v[220:223], v[96:99]
	v_mfma_f32_16x16x32_bf16 v[84:87], v[148:151], v[228:231], v[84:87]
	v_mfma_f32_16x16x32_bf16 v[80:83], v[156:159], v[228:231], v[80:83]
	v_mfma_f32_16x16x32_bf16 v[108:111], v[160:163], v[186:189], v[108:111]
	v_mfma_f32_16x16x32_bf16 v[104:107], v[168:171], v[186:189], v[104:107]
	v_mfma_f32_16x16x32_bf16 v[92:95], v[160:163], v[194:197], v[92:95]
	v_mfma_f32_16x16x32_bf16 v[88:91], v[168:171], v[194:197], v[88:91]
	v_mfma_f32_16x16x32_bf16 v[76:79], v[160:163], v[202:205], v[76:79]
	v_mfma_f32_16x16x32_bf16 v[72:75], v[168:171], v[202:205], v[72:75]
	v_mfma_f32_16x16x32_bf16 v[68:71], v[160:163], v[224:227], v[68:71]
	v_mfma_f32_16x16x32_bf16 v[64:67], v[168:171], v[224:227], v[64:67]
	v_mfma_f32_16x16x32_bf16 v[108:111], v[164:167], v[190:193], v[108:111]
	v_mfma_f32_16x16x32_bf16 v[104:107], v[172:175], v[190:193], v[104:107]
	v_mfma_f32_16x16x32_bf16 v[92:95], v[164:167], v[198:201], v[92:95]
	v_mfma_f32_16x16x32_bf16 v[88:91], v[172:175], v[198:201], v[88:91]
	v_mfma_f32_16x16x32_bf16 v[76:79], v[164:167], v[220:223], v[76:79]
	v_mfma_f32_16x16x32_bf16 v[72:75], v[172:175], v[220:223], v[72:75]
	v_mfma_f32_16x16x32_bf16 v[68:71], v[164:167], v[228:231], v[68:71]
	v_mfma_f32_16x16x32_bf16 v[64:67], v[172:175], v[228:231], v[64:67]
	s_setprio 0
	s_barrier
	s_mov_b32 m0, s5
	v_lshl_add_u64 v[232:233], s[2:3], 0, v[176:177]
	s_add_u32 s96, s2, 0x40000
	ds_read_b128 v[186:189], v139 offset:16384
	ds_read_b128 v[190:193], v139 offset:17408
	ds_read_b128 v[194:197], v139 offset:18432
	ds_read_b128 v[198:201], v139 offset:19456
	ds_read_b128 v[202:205], v139 offset:20480
	ds_read_b128 v[220:223], v139 offset:21504
	ds_read_b128 v[224:227], v139 offset:22528
	ds_read_b128 v[228:231], v139 offset:23552
	global_load_lds_dwordx4 v[232:233], off
	v_lshl_add_u64 v[234:235], s[2:3], 0, v[128:129]
	s_mov_b32 m0, s22
	s_addc_u32 s97, s3, 0
	global_load_lds_dwordx4 v[234:235], off
	s_mov_b32 m0, s23
	v_lshl_add_u64 v[238:239], s[6:7], 0, v[130:131]
	global_load_lds_dwordx4 v176, s[96:97]
	s_mov_b32 m0, s24
	s_nop 0
	global_load_lds_dwordx4 v128, s[96:97]
	v_lshl_add_u64 v[236:237], s[6:7], 0, v[132:133]
	s_mov_b32 m0, s20
	s_nop 0
	global_load_lds_dwordx4 v[236:237], off
	s_mov_b32 m0, s25
	s_nop 0
	global_load_lds_dwordx4 v[238:239], off
	s_waitcnt vmcnt(8)
	s_waitcnt lgkmcnt(0)
	s_barrier
	s_setprio 1
	s_waitcnt lgkmcnt(0)
	v_mfma_f32_16x16x32_bf16 v[60:63], v[144:147], v[186:189], v[60:63]
	v_mfma_f32_16x16x32_bf16 v[56:59], v[152:155], v[186:189], v[56:59]
	v_mfma_f32_16x16x32_bf16 v[52:55], v[144:147], v[194:197], v[52:55]
	v_mfma_f32_16x16x32_bf16 v[48:51], v[152:155], v[194:197], v[48:51]
	v_mfma_f32_16x16x32_bf16 v[36:39], v[144:147], v[202:205], v[36:39]
	v_mfma_f32_16x16x32_bf16 v[32:35], v[152:155], v[202:205], v[32:35]
	v_mfma_f32_16x16x32_bf16 v[20:23], v[144:147], v[224:227], v[20:23]
	v_mfma_f32_16x16x32_bf16 v[16:19], v[152:155], v[224:227], v[16:19]
	v_mfma_f32_16x16x32_bf16 v[60:63], v[148:151], v[190:193], v[60:63]
	v_mfma_f32_16x16x32_bf16 v[56:59], v[156:159], v[190:193], v[56:59]
	v_mfma_f32_16x16x32_bf16 v[52:55], v[148:151], v[198:201], v[52:55]
	v_mfma_f32_16x16x32_bf16 v[48:51], v[156:159], v[198:201], v[48:51]
	v_mfma_f32_16x16x32_bf16 v[36:39], v[148:151], v[220:223], v[36:39]
	v_mfma_f32_16x16x32_bf16 v[32:35], v[156:159], v[220:223], v[32:35]
	v_mfma_f32_16x16x32_bf16 v[20:23], v[148:151], v[228:231], v[20:23]
	v_mfma_f32_16x16x32_bf16 v[16:19], v[156:159], v[228:231], v[16:19]
	v_mfma_f32_16x16x32_bf16 v[44:47], v[160:163], v[186:189], v[44:47]
	v_mfma_f32_16x16x32_bf16 v[40:43], v[168:171], v[186:189], v[40:43]
	v_mfma_f32_16x16x32_bf16 v[28:31], v[160:163], v[194:197], v[28:31]
	v_mfma_f32_16x16x32_bf16 v[24:27], v[168:171], v[194:197], v[24:27]
	v_mfma_f32_16x16x32_bf16 v[12:15], v[160:163], v[202:205], v[12:15]
	v_mfma_f32_16x16x32_bf16 v[8:11], v[168:171], v[202:205], v[8:11]
	v_mfma_f32_16x16x32_bf16 v[4:7], v[160:163], v[224:227], v[4:7]
	v_mfma_f32_16x16x32_bf16 v[0:3], v[168:171], v[224:227], v[0:3]
	v_mfma_f32_16x16x32_bf16 v[44:47], v[164:167], v[190:193], v[44:47]
	v_mfma_f32_16x16x32_bf16 v[40:43], v[172:175], v[190:193], v[40:43]
	v_mfma_f32_16x16x32_bf16 v[28:31], v[164:167], v[198:201], v[28:31]
	v_mfma_f32_16x16x32_bf16 v[24:27], v[172:175], v[198:201], v[24:27]
	v_mfma_f32_16x16x32_bf16 v[12:15], v[164:167], v[220:223], v[12:15]
	v_mfma_f32_16x16x32_bf16 v[8:11], v[172:175], v[220:223], v[8:11]
	v_mfma_f32_16x16x32_bf16 v[4:7], v[164:167], v[228:231], v[4:7]
	v_mfma_f32_16x16x32_bf16 v[0:3], v[172:175], v[228:231], v[0:3]
	s_setprio 0
	s_barrier
	v_or_b32_e32 v143, 0x18000, v140
	v_add_u32_e32 v148, 0x18400, v140
	ds_read_b128 v[144:147], v143
	ds_read_b128 v[148:151], v148
	v_add_u32_e32 v143, 0x18800, v140
	v_add_u32_e32 v156, 0x18c00, v140
	ds_read_b128 v[152:155], v143
	ds_read_b128 v[156:159], v156
	v_or_b32_e32 v143, 0x1c000, v140
	v_add_u32_e32 v164, 0x1c400, v140
	ds_read_b128 v[160:163], v143
	ds_read_b128 v[164:167], v164
	v_add_u32_e32 v143, 0x1c800, v140
	v_add_u32_e32 v172, 0x1cc00, v140
	ds_read_b128 v[168:171], v143
	ds_read_b128 v[172:175], v172
	s_add_u32 s6, s6, 0x40000
	s_addc_u32 s7, s7, 0
	s_mov_b32 m0, s26
	ds_read_b128 v[186:189], v139 offset:32768
	ds_read_b128 v[190:193], v139 offset:33792
	ds_read_b128 v[194:197], v139 offset:34816
	ds_read_b128 v[198:201], v139 offset:35840
	ds_read_b128 v[202:205], v139 offset:36864
	ds_read_b128 v[220:223], v139 offset:37888
	ds_read_b128 v[224:227], v139 offset:38912
	ds_read_b128 v[228:231], v139 offset:39936
	global_load_lds_dwordx4 v132, s[6:7]
	v_lshl_add_u64 v[240:241], s[6:7], 0, v[130:131]
	s_mov_b32 m0, s27
	s_nop 0
	global_load_lds_dwordx4 v[240:241], off
	s_waitcnt vmcnt(8)
	s_waitcnt lgkmcnt(0)
	s_barrier
	s_setprio 1
	s_waitcnt lgkmcnt(0)
	v_mfma_f32_16x16x32_bf16 v[124:127], v[144:147], v[186:189], v[124:127]
	v_mfma_f32_16x16x32_bf16 v[120:123], v[152:155], v[186:189], v[120:123]
	v_mfma_f32_16x16x32_bf16 v[116:119], v[144:147], v[194:197], v[116:119]
	v_mfma_f32_16x16x32_bf16 v[112:115], v[152:155], v[194:197], v[112:115]
	v_mfma_f32_16x16x32_bf16 v[100:103], v[144:147], v[202:205], v[100:103]
	v_mfma_f32_16x16x32_bf16 v[96:99], v[152:155], v[202:205], v[96:99]
	v_mfma_f32_16x16x32_bf16 v[84:87], v[144:147], v[224:227], v[84:87]
	v_mfma_f32_16x16x32_bf16 v[80:83], v[152:155], v[224:227], v[80:83]
	v_mfma_f32_16x16x32_bf16 v[124:127], v[148:151], v[190:193], v[124:127]
	v_mfma_f32_16x16x32_bf16 v[120:123], v[156:159], v[190:193], v[120:123]
	v_mfma_f32_16x16x32_bf16 v[116:119], v[148:151], v[198:201], v[116:119]
	v_mfma_f32_16x16x32_bf16 v[112:115], v[156:159], v[198:201], v[112:115]
	v_mfma_f32_16x16x32_bf16 v[100:103], v[148:151], v[220:223], v[100:103]
	v_mfma_f32_16x16x32_bf16 v[96:99], v[156:159], v[220:223], v[96:99]
	v_mfma_f32_16x16x32_bf16 v[84:87], v[148:151], v[228:231], v[84:87]
	v_mfma_f32_16x16x32_bf16 v[80:83], v[156:159], v[228:231], v[80:83]
	v_mfma_f32_16x16x32_bf16 v[108:111], v[160:163], v[186:189], v[108:111]
	v_mfma_f32_16x16x32_bf16 v[104:107], v[168:171], v[186:189], v[104:107]
	v_mfma_f32_16x16x32_bf16 v[92:95], v[160:163], v[194:197], v[92:95]
	v_mfma_f32_16x16x32_bf16 v[88:91], v[168:171], v[194:197], v[88:91]
	v_mfma_f32_16x16x32_bf16 v[76:79], v[160:163], v[202:205], v[76:79]
	v_mfma_f32_16x16x32_bf16 v[72:75], v[168:171], v[202:205], v[72:75]
	v_mfma_f32_16x16x32_bf16 v[68:71], v[160:163], v[224:227], v[68:71]
	v_mfma_f32_16x16x32_bf16 v[64:67], v[168:171], v[224:227], v[64:67]
	v_mfma_f32_16x16x32_bf16 v[108:111], v[164:167], v[190:193], v[108:111]
	v_mfma_f32_16x16x32_bf16 v[104:107], v[172:175], v[190:193], v[104:107]
	v_mfma_f32_16x16x32_bf16 v[92:95], v[164:167], v[198:201], v[92:95]
	v_mfma_f32_16x16x32_bf16 v[88:91], v[172:175], v[198:201], v[88:91]
	v_mfma_f32_16x16x32_bf16 v[76:79], v[164:167], v[220:223], v[76:79]
	v_mfma_f32_16x16x32_bf16 v[72:75], v[172:175], v[220:223], v[72:75]
	v_mfma_f32_16x16x32_bf16 v[68:71], v[164:167], v[228:231], v[68:71]
	v_mfma_f32_16x16x32_bf16 v[64:67], v[172:175], v[228:231], v[64:67]
	s_setprio 0
	s_barrier
	s_mov_b32 m0, s28
	v_lshl_add_u64 v[232:233], v[232:233], 0, s[0:1]
	s_add_u32 s2, s2, 0x40080
	ds_read_b128 v[186:189], v139 offset:49152
	ds_read_b128 v[190:193], v139 offset:50176
	ds_read_b128 v[194:197], v139 offset:51200
	ds_read_b128 v[198:201], v139 offset:52224
	ds_read_b128 v[202:205], v139 offset:53248
	ds_read_b128 v[220:223], v139 offset:54272
	ds_read_b128 v[224:227], v139 offset:55296
	ds_read_b128 v[228:231], v139 offset:56320
	global_load_lds_dwordx4 v[232:233], off
	v_lshl_add_u64 v[232:233], v[234:235], 0, s[0:1]
	s_mov_b32 m0, s29
	s_addc_u32 s3, s3, 0
	global_load_lds_dwordx4 v[232:233], off
	s_mov_b32 m0, s34
	s_nop 0
	global_load_lds_dwordx4 v176, s[2:3]
	s_mov_b32 m0, s35
	s_nop 0
	global_load_lds_dwordx4 v128, s[2:3]
	v_lshl_add_u64 v[232:233], v[236:237], 0, s[0:1]
	s_mov_b32 m0, s30
	s_nop 0
	global_load_lds_dwordx4 v[232:233], off
	v_lshl_add_u64 v[232:233], v[238:239], 0, s[0:1]
	s_mov_b32 m0, s31
	s_nop 0
	global_load_lds_dwordx4 v[232:233], off
	s_waitcnt vmcnt(8)
	s_waitcnt lgkmcnt(0)
	s_barrier
	s_setprio 1
	s_waitcnt lgkmcnt(0)
	v_mfma_f32_16x16x32_bf16 v[60:63], v[144:147], v[186:189], v[60:63]
	v_mfma_f32_16x16x32_bf16 v[56:59], v[152:155], v[186:189], v[56:59]
	v_mfma_f32_16x16x32_bf16 v[52:55], v[144:147], v[194:197], v[52:55]
	v_mfma_f32_16x16x32_bf16 v[48:51], v[152:155], v[194:197], v[48:51]
	v_mfma_f32_16x16x32_bf16 v[36:39], v[144:147], v[202:205], v[36:39]
	v_mfma_f32_16x16x32_bf16 v[32:35], v[152:155], v[202:205], v[32:35]
	v_mfma_f32_16x16x32_bf16 v[20:23], v[144:147], v[224:227], v[20:23]
	v_mfma_f32_16x16x32_bf16 v[16:19], v[152:155], v[224:227], v[16:19]
	v_mfma_f32_16x16x32_bf16 v[60:63], v[148:151], v[190:193], v[60:63]
	v_mfma_f32_16x16x32_bf16 v[56:59], v[156:159], v[190:193], v[56:59]
	v_mfma_f32_16x16x32_bf16 v[52:55], v[148:151], v[198:201], v[52:55]
	v_mfma_f32_16x16x32_bf16 v[48:51], v[156:159], v[198:201], v[48:51]
	v_mfma_f32_16x16x32_bf16 v[36:39], v[148:151], v[220:223], v[36:39]
	v_mfma_f32_16x16x32_bf16 v[32:35], v[156:159], v[220:223], v[32:35]
	v_mfma_f32_16x16x32_bf16 v[20:23], v[148:151], v[228:231], v[20:23]
	v_mfma_f32_16x16x32_bf16 v[16:19], v[156:159], v[228:231], v[16:19]
	v_mfma_f32_16x16x32_bf16 v[44:47], v[160:163], v[186:189], v[44:47]
	v_mfma_f32_16x16x32_bf16 v[40:43], v[168:171], v[186:189], v[40:43]
	v_mfma_f32_16x16x32_bf16 v[28:31], v[160:163], v[194:197], v[28:31]
	v_mfma_f32_16x16x32_bf16 v[24:27], v[168:171], v[194:197], v[24:27]
	v_mfma_f32_16x16x32_bf16 v[12:15], v[160:163], v[202:205], v[12:15]
	v_mfma_f32_16x16x32_bf16 v[8:11], v[168:171], v[202:205], v[8:11]
	v_mfma_f32_16x16x32_bf16 v[4:7], v[160:163], v[224:227], v[4:7]
	v_mfma_f32_16x16x32_bf16 v[0:3], v[168:171], v[224:227], v[0:3]
	v_mfma_f32_16x16x32_bf16 v[44:47], v[164:167], v[190:193], v[44:47]
	v_mfma_f32_16x16x32_bf16 v[40:43], v[172:175], v[190:193], v[40:43]
	v_mfma_f32_16x16x32_bf16 v[28:31], v[164:167], v[198:201], v[28:31]
	v_mfma_f32_16x16x32_bf16 v[24:27], v[172:175], v[198:201], v[24:27]
	v_mfma_f32_16x16x32_bf16 v[12:15], v[164:167], v[220:223], v[12:15]
	v_mfma_f32_16x16x32_bf16 v[8:11], v[172:175], v[220:223], v[8:11]
	v_mfma_f32_16x16x32_bf16 v[4:7], v[164:167], v[228:231], v[4:7]
	v_mfma_f32_16x16x32_bf16 v[0:3], v[172:175], v[228:231], v[0:3]
	s_setprio 0
	s_barrier
	s_add_i32 s95, s95, 2
	s_add_u32 s90, s90, 0x100
	s_addc_u32 s91, s91, 0
	s_add_u32 s92, s92, 0x100
	s_addc_u32 s94, s94, 0
	s_cmp_gt_u32 s95, 13
	s_cbranch_scc0 .LBB0_438
	s_and_b64 vcc, exec, s[74:75]
	s_cbranch_vccz .LBB0_441
	s_barrier

.LBB0_462:
	v_or_b32_e32 v147, 0x10000, v145
	v_add_u32_e32 v152, 0x10400, v145
	ds_read_b128 v[148:151], v147
	ds_read_b128 v[152:155], v152
	v_add_u32_e32 v147, 0x10800, v145
	v_add_u32_e32 v160, 0x10c00, v145
	ds_read_b128 v[156:159], v147
	ds_read_b128 v[160:163], v160
	v_or_b32_e32 v147, 0x14000, v145
	v_add_u32_e32 v168, 0x14400, v145
	ds_read_b128 v[164:167], v147
	ds_read_b128 v[168:171], v168
	v_add_u32_e32 v147, 0x14800, v145
	v_add_u32_e32 v186, 0x14c00, v145
	ds_read_b128 v[172:175], v147
	ds_read_b128 v[186:189], v186
	s_add_u32 s2, s90, 0xfffc0080
	s_addc_u32 s3, s91, -1
	s_cmp_eq_u32 s95, 12
	s_cselect_b32 s7, s72, s3
	s_cselect_b32 s6, s75, s2
	s_cselect_b32 s3, s5, s94
	s_cselect_b32 s2, s85, s92
	s_add_i32 m0, s19, 0xc000
	ds_read_b128 v[190:193], v144
	ds_read_b128 v[194:197], v144 offset:1024
	ds_read_b128 v[198:201], v144 offset:2048
	ds_read_b128 v[202:205], v144 offset:3072
	ds_read_b128 v[220:223], v144 offset:4096
	ds_read_b128 v[224:227], v144 offset:5120
	ds_read_b128 v[228:231], v144 offset:6144
	ds_read_b128 v[232:235], v144 offset:7168
	global_load_lds_dwordx4 v138, s[90:91]
	s_add_i32 m0, s19, 0xe000
	s_nop 0
	global_load_lds_dwordx4 v140, s[90:91]
	s_waitcnt vmcnt(8)
	s_waitcnt lgkmcnt(0)
	s_barrier
	s_setprio 1
	s_waitcnt lgkmcnt(0)
	v_mfma_f32_16x16x32_bf16 v[124:127], v[148:151], v[190:193], v[124:127]
	v_mfma_f32_16x16x32_bf16 v[120:123], v[156:159], v[190:193], v[120:123]
	v_mfma_f32_16x16x32_bf16 v[116:119], v[148:151], v[198:201], v[116:119]
	v_mfma_f32_16x16x32_bf16 v[112:115], v[156:159], v[198:201], v[112:115]
	v_mfma_f32_16x16x32_bf16 v[100:103], v[148:151], v[220:223], v[100:103]
	v_mfma_f32_16x16x32_bf16 v[96:99], v[156:159], v[220:223], v[96:99]
	v_mfma_f32_16x16x32_bf16 v[84:87], v[148:151], v[228:231], v[84:87]
	v_mfma_f32_16x16x32_bf16 v[80:83], v[156:159], v[228:231], v[80:83]
	v_mfma_f32_16x16x32_bf16 v[124:127], v[152:155], v[194:197], v[124:127]
	v_mfma_f32_16x16x32_bf16 v[120:123], v[160:163], v[194:197], v[120:123]
	v_mfma_f32_16x16x32_bf16 v[116:119], v[152:155], v[202:205], v[116:119]
	v_mfma_f32_16x16x32_bf16 v[112:115], v[160:163], v[202:205], v[112:115]
	v_mfma_f32_16x16x32_bf16 v[100:103], v[152:155], v[224:227], v[100:103]
	v_mfma_f32_16x16x32_bf16 v[96:99], v[160:163], v[224:227], v[96:99]
	v_mfma_f32_16x16x32_bf16 v[84:87], v[152:155], v[232:235], v[84:87]
	v_mfma_f32_16x16x32_bf16 v[80:83], v[160:163], v[232:235], v[80:83]
	v_mfma_f32_16x16x32_bf16 v[108:111], v[164:167], v[190:193], v[108:111]
	v_mfma_f32_16x16x32_bf16 v[104:107], v[172:175], v[190:193], v[104:107]
	v_mfma_f32_16x16x32_bf16 v[92:95], v[164:167], v[198:201], v[92:95]
	v_mfma_f32_16x16x32_bf16 v[88:91], v[172:175], v[198:201], v[88:91]
	v_mfma_f32_16x16x32_bf16 v[76:79], v[164:167], v[220:223], v[76:79]
	v_mfma_f32_16x16x32_bf16 v[72:75], v[172:175], v[220:223], v[72:75]
	v_mfma_f32_16x16x32_bf16 v[68:71], v[164:167], v[228:231], v[68:71]
	v_mfma_f32_16x16x32_bf16 v[64:67], v[172:175], v[228:231], v[64:67]
	v_mfma_f32_16x16x32_bf16 v[108:111], v[168:171], v[194:197], v[108:111]
	v_mfma_f32_16x16x32_bf16 v[104:107], v[186:189], v[194:197], v[104:107]
	v_mfma_f32_16x16x32_bf16 v[92:95], v[168:171], v[202:205], v[92:95]
	v_mfma_f32_16x16x32_bf16 v[88:91], v[186:189], v[202:205], v[88:91]
	v_mfma_f32_16x16x32_bf16 v[76:79], v[168:171], v[224:227], v[76:79]
	v_mfma_f32_16x16x32_bf16 v[72:75], v[186:189], v[224:227], v[72:75]
	v_mfma_f32_16x16x32_bf16 v[68:71], v[168:171], v[232:235], v[68:71]
	v_mfma_f32_16x16x32_bf16 v[64:67], v[186:189], v[232:235], v[64:67]
	s_setprio 0
	s_barrier
	s_mov_b32 m0, s20
	v_lshl_add_u64 v[236:237], s[2:3], 0, v[130:131]
	s_add_u32 s96, s2, 0x40000
	ds_read_b128 v[190:193], v144 offset:16384
	ds_read_b128 v[194:197], v144 offset:17408
	ds_read_b128 v[198:201], v144 offset:18432
	ds_read_b128 v[202:205], v144 offset:19456
	ds_read_b128 v[220:223], v144 offset:20480
	ds_read_b128 v[224:227], v144 offset:21504
	ds_read_b128 v[228:231], v144 offset:22528
	ds_read_b128 v[232:235], v144 offset:23552
	global_load_lds_dwordx4 v[236:237], off
	v_lshl_add_u64 v[238:239], s[2:3], 0, v[134:135]
	s_mov_b32 m0, s21
	s_addc_u32 s97, s3, 0
	global_load_lds_dwordx4 v[238:239], off
	s_mov_b32 m0, s22
	v_lshl_add_u64 v[242:243], s[6:7], 0, v[132:133]
	global_load_lds_dwordx4 v130, s[96:97]
	s_mov_b32 m0, s23
	s_nop 0
	global_load_lds_dwordx4 v134, s[96:97]
	v_lshl_add_u64 v[240:241], s[6:7], 0, v[128:129]
	s_mov_b32 m0, s19
	s_nop 0
	global_load_lds_dwordx4 v[240:241], off
	s_mov_b32 m0, s24
	s_nop 0
	global_load_lds_dwordx4 v[242:243], off
	s_waitcnt vmcnt(8)
	s_waitcnt lgkmcnt(0)
	s_barrier
	s_setprio 1
	s_waitcnt lgkmcnt(0)
	v_mfma_f32_16x16x32_bf16 v[60:63], v[148:151], v[190:193], v[60:63]
	v_mfma_f32_16x16x32_bf16 v[56:59], v[156:159], v[190:193], v[56:59]
	v_mfma_f32_16x16x32_bf16 v[52:55], v[148:151], v[198:201], v[52:55]
	v_mfma_f32_16x16x32_bf16 v[48:51], v[156:159], v[198:201], v[48:51]
	v_mfma_f32_16x16x32_bf16 v[36:39], v[148:151], v[220:223], v[36:39]
	v_mfma_f32_16x16x32_bf16 v[32:35], v[156:159], v[220:223], v[32:35]
	v_mfma_f32_16x16x32_bf16 v[20:23], v[148:151], v[228:231], v[20:23]
	v_mfma_f32_16x16x32_bf16 v[16:19], v[156:159], v[228:231], v[16:19]
	v_mfma_f32_16x16x32_bf16 v[60:63], v[152:155], v[194:197], v[60:63]
	v_mfma_f32_16x16x32_bf16 v[56:59], v[160:163], v[194:197], v[56:59]
	v_mfma_f32_16x16x32_bf16 v[52:55], v[152:155], v[202:205], v[52:55]
	v_mfma_f32_16x16x32_bf16 v[48:51], v[160:163], v[202:205], v[48:51]
	v_mfma_f32_16x16x32_bf16 v[36:39], v[152:155], v[224:227], v[36:39]
	v_mfma_f32_16x16x32_bf16 v[32:35], v[160:163], v[224:227], v[32:35]
	v_mfma_f32_16x16x32_bf16 v[20:23], v[152:155], v[232:235], v[20:23]
	v_mfma_f32_16x16x32_bf16 v[16:19], v[160:163], v[232:235], v[16:19]
	v_mfma_f32_16x16x32_bf16 v[44:47], v[164:167], v[190:193], v[44:47]
	v_mfma_f32_16x16x32_bf16 v[40:43], v[172:175], v[190:193], v[40:43]
	v_mfma_f32_16x16x32_bf16 v[28:31], v[164:167], v[198:201], v[28:31]
	v_mfma_f32_16x16x32_bf16 v[24:27], v[172:175], v[198:201], v[24:27]
	v_mfma_f32_16x16x32_bf16 v[12:15], v[164:167], v[220:223], v[12:15]
	v_mfma_f32_16x16x32_bf16 v[8:11], v[172:175], v[220:223], v[8:11]
	v_mfma_f32_16x16x32_bf16 v[4:7], v[164:167], v[228:231], v[4:7]
	v_mfma_f32_16x16x32_bf16 v[0:3], v[172:175], v[228:231], v[0:3]
	v_mfma_f32_16x16x32_bf16 v[44:47], v[168:171], v[194:197], v[44:47]
	v_mfma_f32_16x16x32_bf16 v[40:43], v[186:189], v[194:197], v[40:43]
	v_mfma_f32_16x16x32_bf16 v[28:31], v[168:171], v[202:205], v[28:31]
	v_mfma_f32_16x16x32_bf16 v[24:27], v[186:189], v[202:205], v[24:27]
	v_mfma_f32_16x16x32_bf16 v[12:15], v[168:171], v[224:227], v[12:15]
	v_mfma_f32_16x16x32_bf16 v[8:11], v[186:189], v[224:227], v[8:11]
	v_mfma_f32_16x16x32_bf16 v[4:7], v[168:171], v[232:235], v[4:7]
	v_mfma_f32_16x16x32_bf16 v[0:3], v[186:189], v[232:235], v[0:3]
	s_setprio 0
	s_barrier
	v_or_b32_e32 v147, 0x18000, v145
	v_add_u32_e32 v152, 0x18400, v145
	ds_read_b128 v[148:151], v147
	ds_read_b128 v[152:155], v152
	v_add_u32_e32 v147, 0x18800, v145
	v_add_u32_e32 v160, 0x18c00, v145
	ds_read_b128 v[156:159], v147
	ds_read_b128 v[160:163], v160
	v_or_b32_e32 v147, 0x1c000, v145
	v_add_u32_e32 v168, 0x1c400, v145
	ds_read_b128 v[164:167], v147
	ds_read_b128 v[168:171], v168
	v_add_u32_e32 v147, 0x1c800, v145
	v_add_u32_e32 v186, 0x1cc00, v145
	ds_read_b128 v[172:175], v147
	ds_read_b128 v[186:189], v186
	s_add_u32 s6, s6, 0x40000
	s_addc_u32 s7, s7, 0
	s_mov_b32 m0, s25
	ds_read_b128 v[190:193], v144 offset:32768
	ds_read_b128 v[194:197], v144 offset:33792
	ds_read_b128 v[198:201], v144 offset:34816
	ds_read_b128 v[202:205], v144 offset:35840
	ds_read_b128 v[220:223], v144 offset:36864
	ds_read_b128 v[224:227], v144 offset:37888
	ds_read_b128 v[228:231], v144 offset:38912
	ds_read_b128 v[232:235], v144 offset:39936
	global_load_lds_dwordx4 v128, s[6:7]
	v_lshl_add_u64 v[244:245], s[6:7], 0, v[132:133]
	s_mov_b32 m0, s26
	s_nop 0
	global_load_lds_dwordx4 v[244:245], off
	s_waitcnt vmcnt(8)
	s_waitcnt lgkmcnt(0)
	s_barrier
	s_setprio 1
	s_waitcnt lgkmcnt(0)
	v_mfma_f32_16x16x32_bf16 v[124:127], v[148:151], v[190:193], v[124:127]
	v_mfma_f32_16x16x32_bf16 v[120:123], v[156:159], v[190:193], v[120:123]
	v_mfma_f32_16x16x32_bf16 v[116:119], v[148:151], v[198:201], v[116:119]
	v_mfma_f32_16x16x32_bf16 v[112:115], v[156:159], v[198:201], v[112:115]
	v_mfma_f32_16x16x32_bf16 v[100:103], v[148:151], v[220:223], v[100:103]
	v_mfma_f32_16x16x32_bf16 v[96:99], v[156:159], v[220:223], v[96:99]
	v_mfma_f32_16x16x32_bf16 v[84:87], v[148:151], v[228:231], v[84:87]
	v_mfma_f32_16x16x32_bf16 v[80:83], v[156:159], v[228:231], v[80:83]
	v_mfma_f32_16x16x32_bf16 v[124:127], v[152:155], v[194:197], v[124:127]
	v_mfma_f32_16x16x32_bf16 v[120:123], v[160:163], v[194:197], v[120:123]
	v_mfma_f32_16x16x32_bf16 v[116:119], v[152:155], v[202:205], v[116:119]
	v_mfma_f32_16x16x32_bf16 v[112:115], v[160:163], v[202:205], v[112:115]
	v_mfma_f32_16x16x32_bf16 v[100:103], v[152:155], v[224:227], v[100:103]
	v_mfma_f32_16x16x32_bf16 v[96:99], v[160:163], v[224:227], v[96:99]
	v_mfma_f32_16x16x32_bf16 v[84:87], v[152:155], v[232:235], v[84:87]
	v_mfma_f32_16x16x32_bf16 v[80:83], v[160:163], v[232:235], v[80:83]
	v_mfma_f32_16x16x32_bf16 v[108:111], v[164:167], v[190:193], v[108:111]
	v_mfma_f32_16x16x32_bf16 v[104:107], v[172:175], v[190:193], v[104:107]
	v_mfma_f32_16x16x32_bf16 v[92:95], v[164:167], v[198:201], v[92:95]
	v_mfma_f32_16x16x32_bf16 v[88:91], v[172:175], v[198:201], v[88:91]
	v_mfma_f32_16x16x32_bf16 v[76:79], v[164:167], v[220:223], v[76:79]
	v_mfma_f32_16x16x32_bf16 v[72:75], v[172:175], v[220:223], v[72:75]
	v_mfma_f32_16x16x32_bf16 v[68:71], v[164:167], v[228:231], v[68:71]
	v_mfma_f32_16x16x32_bf16 v[64:67], v[172:175], v[228:231], v[64:67]
	v_mfma_f32_16x16x32_bf16 v[108:111], v[168:171], v[194:197], v[108:111]
	v_mfma_f32_16x16x32_bf16 v[104:107], v[186:189], v[194:197], v[104:107]
	v_mfma_f32_16x16x32_bf16 v[92:95], v[168:171], v[202:205], v[92:95]
	v_mfma_f32_16x16x32_bf16 v[88:91], v[186:189], v[202:205], v[88:91]
	v_mfma_f32_16x16x32_bf16 v[76:79], v[168:171], v[224:227], v[76:79]
	v_mfma_f32_16x16x32_bf16 v[72:75], v[186:189], v[224:227], v[72:75]
	v_mfma_f32_16x16x32_bf16 v[68:71], v[168:171], v[232:235], v[68:71]
	v_mfma_f32_16x16x32_bf16 v[64:67], v[186:189], v[232:235], v[64:67]
	s_setprio 0
	s_barrier
	s_mov_b32 m0, s27
	v_lshl_add_u64 v[236:237], v[236:237], 0, s[0:1]
	s_add_u32 s2, s2, 0x40080
	ds_read_b128 v[190:193], v144 offset:49152
	ds_read_b128 v[194:197], v144 offset:50176
	ds_read_b128 v[198:201], v144 offset:51200
	ds_read_b128 v[202:205], v144 offset:52224
	ds_read_b128 v[220:223], v144 offset:53248
	ds_read_b128 v[224:227], v144 offset:54272
	ds_read_b128 v[228:231], v144 offset:55296
	ds_read_b128 v[232:235], v144 offset:56320
	global_load_lds_dwordx4 v[236:237], off
	v_lshl_add_u64 v[236:237], v[238:239], 0, s[0:1]
	s_mov_b32 m0, s28
	s_addc_u32 s3, s3, 0
	global_load_lds_dwordx4 v[236:237], off
	s_mov_b32 m0, s31
	s_nop 0
	global_load_lds_dwordx4 v130, s[2:3]
	s_mov_b32 m0, s34
	s_nop 0
	global_load_lds_dwordx4 v134, s[2:3]
	v_lshl_add_u64 v[236:237], v[240:241], 0, s[0:1]
	s_mov_b32 m0, s29
	s_nop 0
	global_load_lds_dwordx4 v[236:237], off
	v_lshl_add_u64 v[236:237], v[242:243], 0, s[0:1]
	s_mov_b32 m0, s30
	s_nop 0
	global_load_lds_dwordx4 v[236:237], off
	s_waitcnt vmcnt(8)
	s_waitcnt lgkmcnt(0)
	s_barrier
	s_setprio 1
	s_waitcnt lgkmcnt(0)
	v_mfma_f32_16x16x32_bf16 v[60:63], v[148:151], v[190:193], v[60:63]
	v_mfma_f32_16x16x32_bf16 v[56:59], v[156:159], v[190:193], v[56:59]
	v_mfma_f32_16x16x32_bf16 v[52:55], v[148:151], v[198:201], v[52:55]
	v_mfma_f32_16x16x32_bf16 v[48:51], v[156:159], v[198:201], v[48:51]
	v_mfma_f32_16x16x32_bf16 v[36:39], v[148:151], v[220:223], v[36:39]
	v_mfma_f32_16x16x32_bf16 v[32:35], v[156:159], v[220:223], v[32:35]
	v_mfma_f32_16x16x32_bf16 v[20:23], v[148:151], v[228:231], v[20:23]
	v_mfma_f32_16x16x32_bf16 v[16:19], v[156:159], v[228:231], v[16:19]
	v_mfma_f32_16x16x32_bf16 v[60:63], v[152:155], v[194:197], v[60:63]
	v_mfma_f32_16x16x32_bf16 v[56:59], v[160:163], v[194:197], v[56:59]
	v_mfma_f32_16x16x32_bf16 v[52:55], v[152:155], v[202:205], v[52:55]
	v_mfma_f32_16x16x32_bf16 v[48:51], v[160:163], v[202:205], v[48:51]
	v_mfma_f32_16x16x32_bf16 v[36:39], v[152:155], v[224:227], v[36:39]
	v_mfma_f32_16x16x32_bf16 v[32:35], v[160:163], v[224:227], v[32:35]
	v_mfma_f32_16x16x32_bf16 v[20:23], v[152:155], v[232:235], v[20:23]
	v_mfma_f32_16x16x32_bf16 v[16:19], v[160:163], v[232:235], v[16:19]
	v_mfma_f32_16x16x32_bf16 v[44:47], v[164:167], v[190:193], v[44:47]
	v_mfma_f32_16x16x32_bf16 v[40:43], v[172:175], v[190:193], v[40:43]
	v_mfma_f32_16x16x32_bf16 v[28:31], v[164:167], v[198:201], v[28:31]
	v_mfma_f32_16x16x32_bf16 v[24:27], v[172:175], v[198:201], v[24:27]
	v_mfma_f32_16x16x32_bf16 v[12:15], v[164:167], v[220:223], v[12:15]
	v_mfma_f32_16x16x32_bf16 v[8:11], v[172:175], v[220:223], v[8:11]
	v_mfma_f32_16x16x32_bf16 v[4:7], v[164:167], v[228:231], v[4:7]
	v_mfma_f32_16x16x32_bf16 v[0:3], v[172:175], v[228:231], v[0:3]
	v_mfma_f32_16x16x32_bf16 v[44:47], v[168:171], v[194:197], v[44:47]
	v_mfma_f32_16x16x32_bf16 v[40:43], v[186:189], v[194:197], v[40:43]
	v_mfma_f32_16x16x32_bf16 v[28:31], v[168:171], v[202:205], v[28:31]
	v_mfma_f32_16x16x32_bf16 v[24:27], v[186:189], v[202:205], v[24:27]
	v_mfma_f32_16x16x32_bf16 v[12:15], v[168:171], v[224:227], v[12:15]
	v_mfma_f32_16x16x32_bf16 v[8:11], v[186:189], v[224:227], v[8:11]
	v_mfma_f32_16x16x32_bf16 v[4:7], v[168:171], v[232:235], v[4:7]
	v_mfma_f32_16x16x32_bf16 v[0:3], v[186:189], v[232:235], v[0:3]
	s_setprio 0
	s_barrier
	s_add_i32 s95, s95, 2
	s_add_u32 s90, s90, 0x100
	s_addc_u32 s91, s91, 0
	s_add_u32 s92, s92, 0x100
	s_addc_u32 s94, s94, 0
	s_cmp_gt_u32 s95, 13
	s_cbranch_scc0 .LBB0_462
	s_and_b64 vcc, exec, s[40:41]
	s_cbranch_vccz .LBB0_465
	s_barrier
